# v85 + s_nop 0 between every SALU write of m0 and the following LDS-DMA load (hazard fix, 16 sites)
# baseline (speedup 1.0000x reference)
; #define PG8_STAGE(bufoff, gbase, voff) do { _Pragma("unroll") for (int _i = 0; _i < 2; ++_i) \
;         __builtin_amdgcn_global_load_lds((const unsigned*)((const char*)(gbase) + (voff)[_i]), (PG8_LAS unsigned*)(lds + (bufoff) + ldsw + _i * 8192), 16, 0, 0); } while (0)
; #define PG8_LDA(dst, b, h) do { _Pragma("unroll") for (int m = 0; m < 4; ++m) _Pragma("unroll") for (int k = 0; k < 2; ++k) dst[m][k] = *(const PG8_LAS bf16x8*)(lds + PG8_SA(b, h) + aoff + m * 2048 + k * 1024); } while (0)
; #define PG8_LDB(dst, b, h) do { _Pragma("unroll") for (int n = 0; n < 2; ++n) _Pragma("unroll") for (int k = 0; k < 2; ++k) dst[n][k] = *(const PG8_LAS bf16x8*)(lds + PG8_SB(b, h) + boff + n * 2048 + k * 1024); } while (0)
; #define PG8_MMA(ai, bj, At, Bt) do { __builtin_amdgcn_s_setprio(1); _Pragma("unroll") for (int m = 0; m < 4; ++m) _Pragma("unroll") for (int n = 0; n < 2; ++n) _Pragma("unroll") for (int k = 0; k < 2; ++k) \
;         acc[ai][bj][m][n] = __builtin_amdgcn_mfma_f32_16x16x32_bf16(Bt[n][k], At[m][k], acc[ai][bj][m][n], 0, 0, 0); __builtin_amdgcn_s_setprio(0); } while (0)
; #define PG8_WAIT_V(n) asm volatile("s_waitcnt vmcnt(" #n ")" ::: "memory")
; template <class Epi, class Sched, bool ALIGN_EPI = false, bool SP2 = false>
; __device__ __forceinline__ void gemm_phase(PG8_LAS unsigned char* lds, const Gemm g, const Sched& S, const Epi& E) {
;     ...
;             PG8_LDB(B0, 0, 0); PG8_LDB(B1, 0, 1); PG8_SCHED; PG8_LDA(At, 0, 0); PG8_STAGE(PG8_SA(1, 1), a1 + hstepA, voffA);
;             PG8_WAIT_V(8); PG8_WAIT_L(0); PG8_BAR; PG8_MMA(0, 0, At, B0); PG8_MMA(0, 1, At, B1); PG8_BAR; PG8_SCHED;
;             PG8_LDA(At, 0, 1); PG8_STAGE(PG8_SB(0, 0), b2, voffB); PG8_STAGE(PG8_SB(0, 1), b2 + hstepB, voffB); PG8_STAGE(PG8_SA(0, 0), a2, voffA);
;             PG8_WAIT_V(8); PG8_WAIT_L(0); PG8_BAR; PG8_MMA(1, 0, At, B0); PG8_MMA(1, 1, At, B1); PG8_BAR; PG8_SCHED;
;             PG8_LDB(B0, 1, 0); PG8_LDB(B1, 1, 1); PG8_SCHED; PG8_LDA(At, 1, 0); PG8_STAGE(PG8_SA(0, 1), a2 + hstepA, voffA);
;             PG8_WAIT_V(8); PG8_WAIT_L(0); PG8_BAR; PG8_MMA(0, 0, At, B0); PG8_MMA(0, 1, At, B1); PG8_BAR; PG8_SCHED;
;             PG8_LDA(At, 1, 1); PG8_STAGE(PG8_SB(1, 0), b3, voffB); PG8_STAGE(PG8_SB(1, 1), b3 + hstepB, voffB); PG8_STAGE(PG8_SA(1, 0), a3, voffA);
;             PG8_WAIT_V(8); PG8_WAIT_L(0); PG8_BAR; PG8_MMA(1, 0, At, B0); PG8_MMA(1, 1, At, B1); PG8_BAR; PG8_SCHED;
.LBB0_197:
	s_waitcnt lgkmcnt(0)
	s_add_u32 s66, s60, 0xfffc0080
	s_addc_u32 s67, s61, -1
	s_cmp_eq_u32 s74, 12
	s_cselect_b32 s85, s15, s67
	s_cselect_b32 s84, vcc_lo, s66
	s_cselect_b32 s67, s13, s81
	s_cselect_b32 s66, vcc_hi, s80
	v_lshl_add_u64 v[224:225], s[60:61], 0, v[138:139]
	s_add_i32 m0, s59, 0xc000
	s_nop 0
	global_load_lds_dwordx4 v[224:225], off
	v_lshl_add_u64 v[224:225], s[60:61], 0, v[140:141]
	s_add_i32 m0, s59, 0xe000
	s_nop 0
	global_load_lds_dwordx4 v[224:225], off
	ds_read_b128 v[146:149], v159
	ds_read_b128 v[162:165], v159 offset:1024
	ds_read_b128 v[166:169], v159 offset:2048
	ds_read_b128 v[170:173], v159 offset:3072
	ds_read_b128 v[176:179], v160
	ds_read_b128 v[180:183], v160 offset:1024
	ds_read_b128 v[184:187], v160 offset:2048
	ds_read_b128 v[188:191], v160 offset:3072
	ds_read_b128 v[192:195], v161
	ds_read_b128 v[196:199], v161 offset:1024
	ds_read_b128 v[200:203], v161 offset:2048
	ds_read_b128 v[204:207], v161 offset:3072
	ds_read_b128 v[208:211], v161 offset:4096
	ds_read_b128 v[212:215], v161 offset:5120
	ds_read_b128 v[216:219], v161 offset:6144
	ds_read_b128 v[220:223], v161 offset:7168
	s_waitcnt vmcnt(8)
	s_waitcnt lgkmcnt(0)
	s_barrier
	s_setprio 1
	s_waitcnt lgkmcnt(0)
	v_mfma_f32_16x16x32_bf16 v[124:127], v[146:149], v[192:195], v[124:127]
	v_mfma_f32_16x16x32_bf16 v[120:123], v[166:169], v[192:195], v[120:123]
	v_mfma_f32_16x16x32_bf16 v[116:119], v[146:149], v[200:203], v[116:119]
	v_mfma_f32_16x16x32_bf16 v[112:115], v[166:169], v[200:203], v[112:115]
	v_mfma_f32_16x16x32_bf16 v[108:111], v[146:149], v[208:211], v[108:111]
	v_mfma_f32_16x16x32_bf16 v[104:107], v[166:169], v[208:211], v[104:107]
	v_mfma_f32_16x16x32_bf16 v[100:103], v[146:149], v[216:219], v[100:103]
	v_mfma_f32_16x16x32_bf16 v[96:99], v[166:169], v[216:219], v[96:99]
	v_mfma_f32_16x16x32_bf16 v[124:127], v[162:165], v[196:199], v[124:127]
	v_mfma_f32_16x16x32_bf16 v[120:123], v[170:173], v[196:199], v[120:123]
	v_mfma_f32_16x16x32_bf16 v[116:119], v[162:165], v[204:207], v[116:119]
	v_mfma_f32_16x16x32_bf16 v[112:115], v[170:173], v[204:207], v[112:115]
	v_mfma_f32_16x16x32_bf16 v[108:111], v[162:165], v[212:215], v[108:111]
	v_mfma_f32_16x16x32_bf16 v[104:107], v[170:173], v[212:215], v[104:107]
	v_mfma_f32_16x16x32_bf16 v[100:103], v[162:165], v[220:223], v[100:103]
	v_mfma_f32_16x16x32_bf16 v[96:99], v[170:173], v[220:223], v[96:99]
	s_setprio 0
	s_setprio 1
	v_mfma_f32_16x16x32_bf16 v[68:71], v[176:179], v[192:195], v[68:71]
	v_mfma_f32_16x16x32_bf16 v[64:67], v[184:187], v[192:195], v[64:67]
	v_mfma_f32_16x16x32_bf16 v[56:59], v[176:179], v[200:203], v[56:59]
	v_mfma_f32_16x16x32_bf16 v[48:51], v[184:187], v[200:203], v[48:51]
	v_mfma_f32_16x16x32_bf16 v[44:47], v[176:179], v[208:211], v[44:47]
	v_mfma_f32_16x16x32_bf16 v[40:43], v[184:187], v[208:211], v[40:43]
	v_mfma_f32_16x16x32_bf16 v[36:39], v[176:179], v[216:219], v[36:39]
	v_mfma_f32_16x16x32_bf16 v[32:35], v[184:187], v[216:219], v[32:35]
	v_mfma_f32_16x16x32_bf16 v[68:71], v[180:183], v[196:199], v[68:71]
	v_mfma_f32_16x16x32_bf16 v[64:67], v[188:191], v[196:199], v[64:67]
	v_mfma_f32_16x16x32_bf16 v[56:59], v[180:183], v[204:207], v[56:59]
	v_mfma_f32_16x16x32_bf16 v[48:51], v[188:191], v[204:207], v[48:51]
	v_mfma_f32_16x16x32_bf16 v[44:47], v[180:183], v[212:215], v[44:47]
	v_mfma_f32_16x16x32_bf16 v[40:43], v[188:191], v[212:215], v[40:43]
	v_mfma_f32_16x16x32_bf16 v[36:39], v[180:183], v[220:223], v[36:39]
	v_mfma_f32_16x16x32_bf16 v[32:35], v[188:191], v[220:223], v[32:35]
	s_setprio 0
	s_barrier
	s_add_i32 s75, s38, s27
	v_lshl_add_u64 v[224:225], s[66:67], 0, v[132:133]
	s_mov_b32 m0, s75
	s_nop 0
	global_load_lds_dwordx4 v[224:225], off
	s_add_i32 m0, s75, 0x2000
	s_add_u32 s76, s66, 0x40000
	v_lshl_add_u64 v[226:227], s[66:67], 0, v[128:129]
	s_addc_u32 s77, s67, 0
	s_add_i32 s75, s39, s27
	global_load_lds_dwordx4 v[226:227], off
	v_lshl_add_u64 v[228:229], s[76:77], 0, v[132:133]
	s_mov_b32 m0, s75
	v_lshl_add_u64 v[230:231], s[84:85], 0, v[130:131]
	global_load_lds_dwordx4 v[228:229], off
	v_lshl_add_u64 v[228:229], s[76:77], 0, v[128:129]
	s_add_i32 m0, s75, 0x2000
	s_nop 0
	global_load_lds_dwordx4 v[228:229], off
	v_lshl_add_u64 v[228:229], s[84:85], 0, v[134:135]
	s_mov_b32 m0, s59
	s_nop 0
	global_load_lds_dwordx4 v[228:229], off
	s_mov_b32 m0, s86
	s_nop 0
	global_load_lds_dwordx4 v[230:231], off
	ds_read_b128 v[192:195], v161 offset:16384
	ds_read_b128 v[196:199], v161 offset:17408
	ds_read_b128 v[200:203], v161 offset:18432
	ds_read_b128 v[204:207], v161 offset:19456
	ds_read_b128 v[208:211], v161 offset:20480
	ds_read_b128 v[212:215], v161 offset:21504
	ds_read_b128 v[216:219], v161 offset:22528
	ds_read_b128 v[220:223], v161 offset:23552
	s_waitcnt vmcnt(8)
	s_waitcnt lgkmcnt(0)
	s_barrier
; #define PG8_STAGE(bufoff, gbase, voff) do { _Pragma("unroll") for (int _i = 0; _i < 2; ++_i) \
;         __builtin_amdgcn_global_load_lds((const unsigned*)((const char*)(gbase) + (voff)[_i]), (PG8_LAS unsigned*)(lds + (bufoff) + ldsw + _i * 8192), 16, 0, 0); } while (0)
; #define PG8_LDA(dst, b, h) do { _Pragma("unroll") for (int m = 0; m < 4; ++m) _Pragma("unroll") for (int k = 0; k < 2; ++k) dst[m][k] = *(const PG8_LAS bf16x8*)(lds + PG8_SA(b, h) + aoff + m * 2048 + k * 1024); } while (0)
; #define PG8_LDB(dst, b, h) do { _Pragma("unroll") for (int n = 0; n < 2; ++n) _Pragma("unroll") for (int k = 0; k < 2; ++k) dst[n][k] = *(const PG8_LAS bf16x8*)(lds + PG8_SB(b, h) + boff + n * 2048 + k * 1024); } while (0)
; #define PG8_MMA(ai, bj, At, Bt) do { __builtin_amdgcn_s_setprio(1); _Pragma("unroll") for (int m = 0; m < 4; ++m) _Pragma("unroll") for (int n = 0; n < 2; ++n) _Pragma("unroll") for (int k = 0; k < 2; ++k) \
;         acc[ai][bj][m][n] = __builtin_amdgcn_mfma_f32_16x16x32_bf16(Bt[n][k], At[m][k], acc[ai][bj][m][n], 0, 0, 0); __builtin_amdgcn_s_setprio(0); } while (0)
; #define PG8_WAIT_V(n) asm volatile("s_waitcnt vmcnt(" #n ")" ::: "memory")
; template <class Epi, class Sched, bool ALIGN_EPI = false, bool SP2 = false>
; __device__ __forceinline__ void gemm_phase(PG8_LAS unsigned char* lds, const Gemm g, const Sched& S, const Epi& E) {
;     ...
;             PG8_LDB(B0, 0, 0); PG8_LDB(B1, 0, 1); PG8_SCHED; PG8_LDA(At, 0, 0); PG8_STAGE(PG8_SA(1, 1), a1 + hstepA, voffA);
;             PG8_WAIT_V(8); PG8_WAIT_L(0); PG8_BAR; PG8_MMA(0, 0, At, B0); PG8_MMA(0, 1, At, B1); PG8_BAR; PG8_SCHED;
;             PG8_LDA(At, 0, 1); PG8_STAGE(PG8_SB(0, 0), b2, voffB); PG8_STAGE(PG8_SB(0, 1), b2 + hstepB, voffB); PG8_STAGE(PG8_SA(0, 0), a2, voffA);
;             PG8_WAIT_V(8); PG8_WAIT_L(0); PG8_BAR; PG8_MMA(1, 0, At, B0); PG8_MMA(1, 1, At, B1); PG8_BAR; PG8_SCHED;
;             PG8_LDB(B0, 1, 0); PG8_LDB(B1, 1, 1); PG8_SCHED; PG8_LDA(At, 1, 0); PG8_STAGE(PG8_SA(0, 1), a2 + hstepA, voffA);
;             PG8_WAIT_V(8); PG8_WAIT_L(0); PG8_BAR; PG8_MMA(0, 0, At, B0); PG8_MMA(0, 1, At, B1); PG8_BAR; PG8_SCHED;
;             PG8_LDA(At, 1, 1); PG8_STAGE(PG8_SB(1, 0), b3, voffB); PG8_STAGE(PG8_SB(1, 1), b3 + hstepB, voffB); PG8_STAGE(PG8_SA(1, 0), a3, voffA);
;             PG8_WAIT_V(8); PG8_WAIT_L(0); PG8_BAR; PG8_MMA(1, 0, At, B0); PG8_MMA(1, 1, At, B1); PG8_BAR; PG8_SCHED;
	s_setprio 1
	s_waitcnt lgkmcnt(0)
	v_mfma_f32_16x16x32_bf16 v[92:95], v[146:149], v[192:195], v[92:95]
	v_mfma_f32_16x16x32_bf16 v[88:91], v[166:169], v[192:195], v[88:91]
	v_mfma_f32_16x16x32_bf16 v[84:87], v[146:149], v[200:203], v[84:87]
	v_mfma_f32_16x16x32_bf16 v[80:83], v[166:169], v[200:203], v[80:83]
	v_mfma_f32_16x16x32_bf16 v[76:79], v[146:149], v[208:211], v[76:79]
	v_mfma_f32_16x16x32_bf16 v[72:75], v[166:169], v[208:211], v[72:75]
	v_mfma_f32_16x16x32_bf16 v[60:63], v[146:149], v[216:219], v[60:63]
	v_mfma_f32_16x16x32_bf16 v[52:55], v[166:169], v[216:219], v[52:55]
	v_mfma_f32_16x16x32_bf16 v[92:95], v[162:165], v[196:199], v[92:95]
	v_mfma_f32_16x16x32_bf16 v[88:91], v[170:173], v[196:199], v[88:91]
	v_mfma_f32_16x16x32_bf16 v[84:87], v[162:165], v[204:207], v[84:87]
	v_mfma_f32_16x16x32_bf16 v[80:83], v[170:173], v[204:207], v[80:83]
	v_mfma_f32_16x16x32_bf16 v[76:79], v[162:165], v[212:215], v[76:79]
	v_mfma_f32_16x16x32_bf16 v[72:75], v[170:173], v[212:215], v[72:75]
	v_mfma_f32_16x16x32_bf16 v[60:63], v[162:165], v[220:223], v[60:63]
	v_mfma_f32_16x16x32_bf16 v[52:55], v[170:173], v[220:223], v[52:55]
	s_setprio 0
	s_setprio 1
	v_mfma_f32_16x16x32_bf16 v[28:31], v[176:179], v[192:195], v[28:31]
	v_mfma_f32_16x16x32_bf16 v[24:27], v[184:187], v[192:195], v[24:27]
	v_mfma_f32_16x16x32_bf16 v[20:23], v[176:179], v[200:203], v[20:23]
	v_mfma_f32_16x16x32_bf16 v[16:19], v[184:187], v[200:203], v[16:19]
	v_mfma_f32_16x16x32_bf16 v[12:15], v[176:179], v[208:211], v[12:15]
	v_mfma_f32_16x16x32_bf16 v[8:11], v[184:187], v[208:211], v[8:11]
	v_mfma_f32_16x16x32_bf16 v[4:7], v[176:179], v[216:219], v[4:7]
	v_mfma_f32_16x16x32_bf16 v[0:3], v[184:187], v[216:219], v[0:3]
	v_mfma_f32_16x16x32_bf16 v[28:31], v[180:183], v[196:199], v[28:31]
	v_mfma_f32_16x16x32_bf16 v[24:27], v[188:191], v[196:199], v[24:27]
	v_mfma_f32_16x16x32_bf16 v[20:23], v[180:183], v[204:207], v[20:23]
	v_mfma_f32_16x16x32_bf16 v[16:19], v[188:191], v[204:207], v[16:19]
	v_mfma_f32_16x16x32_bf16 v[12:15], v[180:183], v[212:215], v[12:15]
	v_mfma_f32_16x16x32_bf16 v[8:11], v[188:191], v[212:215], v[8:11]
	v_mfma_f32_16x16x32_bf16 v[4:7], v[180:183], v[220:223], v[4:7]
	v_mfma_f32_16x16x32_bf16 v[0:3], v[188:191], v[220:223], v[0:3]
	s_setprio 0
	s_barrier
	s_add_i32 s75, 0, 0x18000
	s_add_i32 s33, 0, 0x1c000
	v_add_u32_e32 v170, s75, v151
	v_add_u32_e32 v175, s33, v151
	s_add_u32 s76, s84, 0x40000
	s_addc_u32 s77, s85, 0
	s_mov_b32 m0, s87
	v_lshl_add_u64 v[232:233], s[76:77], 0, v[134:135]
	global_load_lds_dwordx4 v[232:233], off
	v_lshl_add_u64 v[232:233], s[76:77], 0, v[130:131]
	s_mov_b32 m0, s88
	s_nop 0
	global_load_lds_dwordx4 v[232:233], off
	ds_read_b128 v[146:149], v170
	ds_read_b128 v[162:165], v170 offset:1024
	ds_read_b128 v[166:169], v170 offset:2048
	ds_read_b128 v[170:173], v170 offset:3072
	ds_read_b128 v[176:179], v175
	ds_read_b128 v[180:183], v175 offset:1024
	ds_read_b128 v[184:187], v175 offset:2048
	ds_read_b128 v[188:191], v175 offset:3072
	ds_read_b128 v[192:195], v161 offset:32768
	ds_read_b128 v[196:199], v161 offset:33792
	ds_read_b128 v[200:203], v161 offset:34816
	ds_read_b128 v[204:207], v161 offset:35840
	ds_read_b128 v[208:211], v161 offset:36864
	ds_read_b128 v[212:215], v161 offset:37888
	ds_read_b128 v[216:219], v161 offset:38912
	ds_read_b128 v[220:223], v161 offset:39936
	s_waitcnt vmcnt(8)
	s_waitcnt lgkmcnt(0)
	s_barrier
	s_setprio 1
	s_waitcnt lgkmcnt(0)
	v_mfma_f32_16x16x32_bf16 v[124:127], v[146:149], v[192:195], v[124:127]
	v_mfma_f32_16x16x32_bf16 v[120:123], v[166:169], v[192:195], v[120:123]
	v_mfma_f32_16x16x32_bf16 v[116:119], v[146:149], v[200:203], v[116:119]
	v_mfma_f32_16x16x32_bf16 v[112:115], v[166:169], v[200:203], v[112:115]
	v_mfma_f32_16x16x32_bf16 v[108:111], v[146:149], v[208:211], v[108:111]
	v_mfma_f32_16x16x32_bf16 v[104:107], v[166:169], v[208:211], v[104:107]
	v_mfma_f32_16x16x32_bf16 v[100:103], v[146:149], v[216:219], v[100:103]
	v_mfma_f32_16x16x32_bf16 v[96:99], v[166:169], v[216:219], v[96:99]
	v_mfma_f32_16x16x32_bf16 v[124:127], v[162:165], v[196:199], v[124:127]
	v_mfma_f32_16x16x32_bf16 v[120:123], v[170:173], v[196:199], v[120:123]
	v_mfma_f32_16x16x32_bf16 v[116:119], v[162:165], v[204:207], v[116:119]
	v_mfma_f32_16x16x32_bf16 v[112:115], v[170:173], v[204:207], v[112:115]
	v_mfma_f32_16x16x32_bf16 v[108:111], v[162:165], v[212:215], v[108:111]
	v_mfma_f32_16x16x32_bf16 v[104:107], v[170:173], v[212:215], v[104:107]
	v_mfma_f32_16x16x32_bf16 v[100:103], v[162:165], v[220:223], v[100:103]
	v_mfma_f32_16x16x32_bf16 v[96:99], v[170:173], v[220:223], v[96:99]
	s_setprio 0
	s_setprio 1
	v_mfma_f32_16x16x32_bf16 v[68:71], v[176:179], v[192:195], v[68:71]
	v_mfma_f32_16x16x32_bf16 v[64:67], v[184:187], v[192:195], v[64:67]
	v_mfma_f32_16x16x32_bf16 v[56:59], v[176:179], v[200:203], v[56:59]
	v_mfma_f32_16x16x32_bf16 v[48:51], v[184:187], v[200:203], v[48:51]
	v_mfma_f32_16x16x32_bf16 v[44:47], v[176:179], v[208:211], v[44:47]
	v_mfma_f32_16x16x32_bf16 v[40:43], v[184:187], v[208:211], v[40:43]
	v_mfma_f32_16x16x32_bf16 v[36:39], v[176:179], v[216:219], v[36:39]
	v_mfma_f32_16x16x32_bf16 v[32:35], v[184:187], v[216:219], v[32:35]
	v_mfma_f32_16x16x32_bf16 v[68:71], v[180:183], v[196:199], v[68:71]
	v_mfma_f32_16x16x32_bf16 v[64:67], v[188:191], v[196:199], v[64:67]
	v_mfma_f32_16x16x32_bf16 v[56:59], v[180:183], v[204:207], v[56:59]
	v_mfma_f32_16x16x32_bf16 v[48:51], v[188:191], v[204:207], v[48:51]
	v_mfma_f32_16x16x32_bf16 v[44:47], v[180:183], v[212:215], v[44:47]
	v_mfma_f32_16x16x32_bf16 v[40:43], v[188:191], v[212:215], v[40:43]
	v_mfma_f32_16x16x32_bf16 v[36:39], v[180:183], v[220:223], v[36:39]
	v_mfma_f32_16x16x32_bf16 v[32:35], v[188:191], v[220:223], v[32:35]
	s_setprio 0
	s_barrier
; #define PG8_STAGE(bufoff, gbase, voff) do { _Pragma("unroll") for (int _i = 0; _i < 2; ++_i) \
;         __builtin_amdgcn_global_load_lds((const unsigned*)((const char*)(gbase) + (voff)[_i]), (PG8_LAS unsigned*)(lds + (bufoff) + ldsw + _i * 8192), 16, 0, 0); } while (0)
; #define PG8_LDA(dst, b, h) do { _Pragma("unroll") for (int m = 0; m < 4; ++m) _Pragma("unroll") for (int k = 0; k < 2; ++k) dst[m][k] = *(const PG8_LAS bf16x8*)(lds + PG8_SA(b, h) + aoff + m * 2048 + k * 1024); } while (0)
; template <class Epi, class Sched, bool ALIGN_EPI = false, bool SP2 = false>
; __device__ __forceinline__ void gemm_phase(PG8_LAS unsigned char* lds, const Gemm g, const Sched& S, const Epi& E) {
;     ...
;         const bool has_next = S.next(ui + 1, nxt);
;         const char* nA = has_next ? (const char*)g.A + (size_t)nxt.pm * tstepA + (size_t)nxt.pn * apn : cA; const char* nB = has_next ? (const char*)g.Bt + (size_t)nxt.pn * tstepB : cB;
;         for (int t = 0; t < nt; t += 2) {
;             const bool last = (t == nt - 2);
;             const char* a1 = cA + (size_t)(t + 1) * kstep;
;             const char* a2 = last ? nA : cA + (size_t)(t + 2) * kstep; const char* b2 = last ? nB : cB + (size_t)(t + 2) * kstep;
;             const char* a3 = a2 + kstep; const char* b3 = b2 + kstep;
;             if (last && has_next) S.a_ready(nxt);
;     ...
;             PG8_LDB(B0, 0, 0); PG8_LDB(B1, 0, 1); PG8_SCHED; PG8_LDA(At, 0, 0); PG8_STAGE(PG8_SA(1, 1), a1 + hstepA, voffA);
;             PG8_WAIT_V(8); PG8_WAIT_L(0); PG8_BAR; PG8_MMA(0, 0, At, B0); PG8_MMA(0, 1, At, B1); PG8_BAR; PG8_SCHED;
;             PG8_LDA(At, 0, 1); PG8_STAGE(PG8_SB(0, 0), b2, voffB); PG8_STAGE(PG8_SB(0, 1), b2 + hstepB, voffB); PG8_STAGE(PG8_SA(0, 0), a2, voffA);
;             PG8_WAIT_V(8); PG8_WAIT_L(0); PG8_BAR; PG8_MMA(1, 0, At, B0); PG8_MMA(1, 1, At, B1); PG8_BAR; PG8_SCHED;
;             PG8_LDB(B0, 1, 0); PG8_LDB(B1, 1, 1); PG8_SCHED; PG8_LDA(At, 1, 0); PG8_STAGE(PG8_SA(0, 1), a2 + hstepA, voffA);
;             PG8_WAIT_V(8); PG8_WAIT_L(0); PG8_BAR; PG8_MMA(0, 0, At, B0); PG8_MMA(0, 1, At, B1); PG8_BAR; PG8_SCHED;
;             PG8_LDA(At, 1, 1); PG8_STAGE(PG8_SB(1, 0), b3, voffB); PG8_STAGE(PG8_SB(1, 1), b3 + hstepB, voffB); PG8_STAGE(PG8_SA(1, 0), a3, voffA);
;             PG8_WAIT_V(8); PG8_WAIT_L(0); PG8_BAR; PG8_MMA(1, 0, At, B0); PG8_MMA(1, 1, At, B1); PG8_BAR; PG8_SCHED;
	s_add_i32 s75, s75, s27
	v_lshl_add_u64 v[224:225], v[224:225], 0, s[8:9]
	s_mov_b32 m0, s75
	s_nop 0
	global_load_lds_dwordx4 v[224:225], off
	s_add_i32 m0, s75, 0x2000
	s_add_u32 s66, s66, 0x40080
	v_lshl_add_u64 v[224:225], v[226:227], 0, s[8:9]
	s_addc_u32 s67, s67, 0
	s_add_i32 s33, s33, s27
	global_load_lds_dwordx4 v[224:225], off
	v_lshl_add_u64 v[224:225], s[66:67], 0, v[132:133]
	s_mov_b32 m0, s33
	s_nop 0
	global_load_lds_dwordx4 v[224:225], off
	v_lshl_add_u64 v[224:225], s[66:67], 0, v[128:129]
	s_add_i32 m0, s33, 0x2000
	s_nop 0
	global_load_lds_dwordx4 v[224:225], off
	v_lshl_add_u64 v[224:225], v[228:229], 0, s[8:9]
	s_mov_b32 m0, s91
	s_nop 0
	global_load_lds_dwordx4 v[224:225], off
	v_lshl_add_u64 v[224:225], v[230:231], 0, s[8:9]
	s_mov_b32 m0, s92
	s_nop 0
	global_load_lds_dwordx4 v[224:225], off
	ds_read_b128 v[192:195], v161 offset:49152
	ds_read_b128 v[196:199], v161 offset:50176
	ds_read_b128 v[200:203], v161 offset:51200
	ds_read_b128 v[204:207], v161 offset:52224
	ds_read_b128 v[208:211], v161 offset:53248
	ds_read_b128 v[212:215], v161 offset:54272
	ds_read_b128 v[216:219], v161 offset:55296
	ds_read_b128 v[220:223], v161 offset:56320
	s_waitcnt vmcnt(8)
	s_waitcnt lgkmcnt(0)
	s_barrier
	s_setprio 1
	s_waitcnt lgkmcnt(0)
	v_mfma_f32_16x16x32_bf16 v[92:95], v[146:149], v[192:195], v[92:95]
	v_mfma_f32_16x16x32_bf16 v[88:91], v[166:169], v[192:195], v[88:91]
	v_mfma_f32_16x16x32_bf16 v[84:87], v[146:149], v[200:203], v[84:87]
	v_mfma_f32_16x16x32_bf16 v[80:83], v[166:169], v[200:203], v[80:83]
	v_mfma_f32_16x16x32_bf16 v[76:79], v[146:149], v[208:211], v[76:79]
	v_mfma_f32_16x16x32_bf16 v[72:75], v[166:169], v[208:211], v[72:75]
	v_mfma_f32_16x16x32_bf16 v[60:63], v[146:149], v[216:219], v[60:63]
	v_mfma_f32_16x16x32_bf16 v[52:55], v[166:169], v[216:219], v[52:55]
	v_mfma_f32_16x16x32_bf16 v[92:95], v[162:165], v[196:199], v[92:95]
	v_mfma_f32_16x16x32_bf16 v[88:91], v[170:173], v[196:199], v[88:91]
	v_mfma_f32_16x16x32_bf16 v[84:87], v[162:165], v[204:207], v[84:87]
	v_mfma_f32_16x16x32_bf16 v[80:83], v[170:173], v[204:207], v[80:83]
	v_mfma_f32_16x16x32_bf16 v[76:79], v[162:165], v[212:215], v[76:79]
	v_mfma_f32_16x16x32_bf16 v[72:75], v[170:173], v[212:215], v[72:75]
	v_mfma_f32_16x16x32_bf16 v[60:63], v[162:165], v[220:223], v[60:63]
	v_mfma_f32_16x16x32_bf16 v[52:55], v[170:173], v[220:223], v[52:55]
	s_setprio 0
	s_setprio 1
	v_mfma_f32_16x16x32_bf16 v[28:31], v[176:179], v[192:195], v[28:31]
	v_mfma_f32_16x16x32_bf16 v[24:27], v[184:187], v[192:195], v[24:27]
	v_mfma_f32_16x16x32_bf16 v[20:23], v[176:179], v[200:203], v[20:23]
	v_mfma_f32_16x16x32_bf16 v[16:19], v[184:187], v[200:203], v[16:19]
	v_mfma_f32_16x16x32_bf16 v[12:15], v[176:179], v[208:211], v[12:15]
	v_mfma_f32_16x16x32_bf16 v[8:11], v[184:187], v[208:211], v[8:11]
	v_mfma_f32_16x16x32_bf16 v[4:7], v[176:179], v[216:219], v[4:7]
	v_mfma_f32_16x16x32_bf16 v[0:3], v[184:187], v[216:219], v[0:3]
	v_mfma_f32_16x16x32_bf16 v[28:31], v[180:183], v[196:199], v[28:31]
	v_mfma_f32_16x16x32_bf16 v[24:27], v[188:191], v[196:199], v[24:27]
	v_mfma_f32_16x16x32_bf16 v[20:23], v[180:183], v[204:207], v[20:23]
	v_mfma_f32_16x16x32_bf16 v[16:19], v[188:191], v[204:207], v[16:19]
	v_mfma_f32_16x16x32_bf16 v[12:15], v[180:183], v[212:215], v[12:15]
	v_mfma_f32_16x16x32_bf16 v[8:11], v[188:191], v[212:215], v[8:11]
	v_mfma_f32_16x16x32_bf16 v[4:7], v[180:183], v[220:223], v[4:7]
	v_mfma_f32_16x16x32_bf16 v[0:3], v[188:191], v[220:223], v[0:3]
	s_setprio 0
	s_barrier
	s_add_i32 s74, s74, 2
	s_add_u32 s60, s60, 0x100
	s_addc_u32 s61, s61, 0
	s_add_u32 s80, s80, 0x100
	s_addc_u32 s81, s81, 0
	s_cmp_gt_u32 s74, 13
	s_cbranch_scc0 .LBB0_197
	s_add_u32 s100, vcc_lo, 0x40080
	s_addc_u32 s101, s15, 0
	s_and_b64 vcc, exec, s[10:11]
	s_cbranch_vccnz .LBB0_203
	v_lshl_add_u64 v[224:225], s[100:101], 0, v[138:139]
	s_add_i32 m0, s59, 0xc000
	v_lshl_add_u64 v[226:227], s[100:101], 0, v[140:141]
	global_load_lds_dwordx4 v[224:225], off
	s_add_i32 m0, s59, 0xe000
	s_nop 0
	global_load_lds_dwordx4 v[226:227], off
	s_and_b32 s13, s73, -4
	s_cmp_lg_u32 s13, 4
	s_cbranch_scc0 .LBB0_204

; #define PG8_STAGE(bufoff, gbase, voff) do { _Pragma("unroll") for (int _i = 0; _i < 2; ++_i) \
;         __builtin_amdgcn_global_load_lds((const unsigned*)((const char*)(gbase) + (voff)[_i]), (PG8_LAS unsigned*)(lds + (bufoff) + ldsw + _i * 8192), 16, 0, 0); } while (0)
; #define PG8_LDA(dst, b, h) do { _Pragma("unroll") for (int m = 0; m < 4; ++m) _Pragma("unroll") for (int k = 0; k < 2; ++k) dst[m][k] = *(const PG8_LAS bf16x8*)(lds + PG8_SA(b, h) + aoff + m * 2048 + k * 1024); } while (0)
; #define PG8_LDB(dst, b, h) do { _Pragma("unroll") for (int n = 0; n < 2; ++n) _Pragma("unroll") for (int k = 0; k < 2; ++k) dst[n][k] = *(const PG8_LAS bf16x8*)(lds + PG8_SB(b, h) + boff + n * 2048 + k * 1024); } while (0)
; #define PG8_MMA(ai, bj, At, Bt) do { __builtin_amdgcn_s_setprio(1); _Pragma("unroll") for (int m = 0; m < 4; ++m) _Pragma("unroll") for (int n = 0; n < 2; ++n) _Pragma("unroll") for (int k = 0; k < 2; ++k) \
;         acc[ai][bj][m][n] = __builtin_amdgcn_mfma_f32_16x16x32_bf16(Bt[n][k], At[m][k], acc[ai][bj][m][n], 0, 0, 0); __builtin_amdgcn_s_setprio(0); } while (0)
; #define PG8_WAIT_V(n) asm volatile("s_waitcnt vmcnt(" #n ")" ::: "memory")
; template <class Epi, class Sched, bool ALIGN_EPI = false, bool SP2 = false>
; __device__ __forceinline__ void gemm_phase(PG8_LAS unsigned char* lds, const Gemm g, const Sched& S, const Epi& E) {
;     ...
;             PG8_LDB(B0, 0, 0); PG8_LDB(B1, 0, 1); PG8_SCHED; PG8_LDA(At, 0, 0); PG8_STAGE(PG8_SA(1, 1), a1 + hstepA, voffA);
;             PG8_WAIT_V(8); PG8_WAIT_L(0); PG8_BAR; PG8_MMA(0, 0, At, B0); PG8_MMA(0, 1, At, B1); PG8_BAR; PG8_SCHED;
;             PG8_LDA(At, 0, 1); PG8_STAGE(PG8_SB(0, 0), b2, voffB); PG8_STAGE(PG8_SB(0, 1), b2 + hstepB, voffB); PG8_STAGE(PG8_SA(0, 0), a2, voffA);
;             PG8_WAIT_V(8); PG8_WAIT_L(0); PG8_BAR; PG8_MMA(1, 0, At, B0); PG8_MMA(1, 1, At, B1); PG8_BAR; PG8_SCHED;
;             PG8_LDB(B0, 1, 0); PG8_LDB(B1, 1, 1); PG8_SCHED; PG8_LDA(At, 1, 0); PG8_STAGE(PG8_SA(0, 1), a2 + hstepA, voffA);
;             PG8_WAIT_V(8); PG8_WAIT_L(0); PG8_BAR; PG8_MMA(0, 0, At, B0); PG8_MMA(0, 1, At, B1); PG8_BAR; PG8_SCHED;
;             PG8_LDA(At, 1, 1); PG8_STAGE(PG8_SB(1, 0), b3, voffB); PG8_STAGE(PG8_SB(1, 1), b3 + hstepB, voffB); PG8_STAGE(PG8_SA(1, 0), a3, voffA);
;             PG8_WAIT_V(8); PG8_WAIT_L(0); PG8_BAR; PG8_MMA(1, 0, At, B0); PG8_MMA(1, 1, At, B1); PG8_BAR; PG8_SCHED;
.Lpeel_p2:
	s_waitcnt lgkmcnt(0)
	ds_read_b128 v[146:149], v159
	ds_read_b128 v[162:165], v159 offset:1024
	ds_read_b128 v[166:169], v159 offset:2048
	ds_read_b128 v[170:173], v159 offset:3072
	ds_read_b128 v[176:179], v160
	ds_read_b128 v[180:183], v160 offset:1024
	ds_read_b128 v[184:187], v160 offset:2048
	ds_read_b128 v[188:191], v160 offset:3072
	s_add_u32 s66, s60, 0xfffc0080
	s_addc_u32 s67, s61, -1
	s_cmp_eq_u32 s74, 12
	s_cselect_b32 s85, s15, s67
	s_cselect_b32 s84, vcc_lo, s66
	s_cselect_b32 s67, s13, s81
	s_cselect_b32 s66, vcc_hi, s80
	ds_read_b128 v[192:195], v161
	ds_read_b128 v[196:199], v161 offset:1024
	ds_read_b128 v[200:203], v161 offset:2048
	ds_read_b128 v[204:207], v161 offset:3072
	ds_read_b128 v[208:211], v161 offset:4096
	ds_read_b128 v[212:215], v161 offset:5120
	ds_read_b128 v[216:219], v161 offset:6144
	ds_read_b128 v[220:223], v161 offset:7168
	s_waitcnt vmcnt(24)
	s_waitcnt lgkmcnt(0)
	s_barrier
	s_setprio 1
	s_waitcnt lgkmcnt(0)
	v_mfma_f32_16x16x32_bf16 v[124:127], v[146:149], v[192:195], 0
	v_mfma_f32_16x16x32_bf16 v[120:123], v[166:169], v[192:195], 0
	v_mfma_f32_16x16x32_bf16 v[116:119], v[146:149], v[200:203], 0
	v_mfma_f32_16x16x32_bf16 v[112:115], v[166:169], v[200:203], 0
	v_mfma_f32_16x16x32_bf16 v[108:111], v[146:149], v[208:211], 0
	v_mfma_f32_16x16x32_bf16 v[104:107], v[166:169], v[208:211], 0
	v_mfma_f32_16x16x32_bf16 v[100:103], v[146:149], v[216:219], 0
	v_mfma_f32_16x16x32_bf16 v[96:99], v[166:169], v[216:219], 0
	v_mfma_f32_16x16x32_bf16 v[124:127], v[162:165], v[196:199], v[124:127]
	v_mfma_f32_16x16x32_bf16 v[120:123], v[170:173], v[196:199], v[120:123]
	v_mfma_f32_16x16x32_bf16 v[116:119], v[162:165], v[204:207], v[116:119]
	v_mfma_f32_16x16x32_bf16 v[112:115], v[170:173], v[204:207], v[112:115]
	v_mfma_f32_16x16x32_bf16 v[108:111], v[162:165], v[212:215], v[108:111]
	v_mfma_f32_16x16x32_bf16 v[104:107], v[170:173], v[212:215], v[104:107]
	v_mfma_f32_16x16x32_bf16 v[100:103], v[162:165], v[220:223], v[100:103]
	v_mfma_f32_16x16x32_bf16 v[96:99], v[170:173], v[220:223], v[96:99]
	s_setprio 0
	s_setprio 1
	v_mfma_f32_16x16x32_bf16 v[68:71], v[176:179], v[192:195], 0
	v_mfma_f32_16x16x32_bf16 v[64:67], v[184:187], v[192:195], 0
	v_mfma_f32_16x16x32_bf16 v[56:59], v[176:179], v[200:203], 0
	v_mfma_f32_16x16x32_bf16 v[48:51], v[184:187], v[200:203], 0
	v_mfma_f32_16x16x32_bf16 v[44:47], v[176:179], v[208:211], 0
	v_mfma_f32_16x16x32_bf16 v[40:43], v[184:187], v[208:211], 0
	v_mfma_f32_16x16x32_bf16 v[36:39], v[176:179], v[216:219], 0
	v_mfma_f32_16x16x32_bf16 v[32:35], v[184:187], v[216:219], 0
	v_mfma_f32_16x16x32_bf16 v[68:71], v[180:183], v[196:199], v[68:71]
	v_mfma_f32_16x16x32_bf16 v[64:67], v[188:191], v[196:199], v[64:67]
	v_mfma_f32_16x16x32_bf16 v[56:59], v[180:183], v[204:207], v[56:59]
	v_mfma_f32_16x16x32_bf16 v[48:51], v[188:191], v[204:207], v[48:51]
	v_mfma_f32_16x16x32_bf16 v[44:47], v[180:183], v[212:215], v[44:47]
	v_mfma_f32_16x16x32_bf16 v[40:43], v[188:191], v[212:215], v[40:43]
	v_mfma_f32_16x16x32_bf16 v[36:39], v[180:183], v[220:223], v[36:39]
	v_mfma_f32_16x16x32_bf16 v[32:35], v[188:191], v[220:223], v[32:35]
	s_setprio 0
	s_barrier
	s_add_i32 s75, s38, s27
	v_lshl_add_u64 v[224:225], s[66:67], 0, v[132:133]
	s_mov_b32 m0, s75
	s_nop 0
	global_load_lds_dwordx4 v[224:225], off
	s_add_i32 m0, s75, 0x2000
	s_add_u32 s76, s66, 0x40000
	v_lshl_add_u64 v[226:227], s[66:67], 0, v[128:129]
	s_addc_u32 s77, s67, 0
	s_add_i32 s75, s39, s27
	global_load_lds_dwordx4 v[226:227], off
	v_lshl_add_u64 v[228:229], s[76:77], 0, v[132:133]
	s_mov_b32 m0, s75
	v_lshl_add_u64 v[230:231], s[84:85], 0, v[130:131]
	global_load_lds_dwordx4 v[228:229], off
	v_lshl_add_u64 v[228:229], s[76:77], 0, v[128:129]
	s_add_i32 m0, s75, 0x2000
	s_nop 0
	global_load_lds_dwordx4 v[228:229], off
	v_lshl_add_u64 v[228:229], s[84:85], 0, v[134:135]
	s_mov_b32 m0, s59
	s_nop 0
	global_load_lds_dwordx4 v[228:229], off
	s_mov_b32 m0, s86
	s_nop 0
	global_load_lds_dwordx4 v[230:231], off
	ds_read_b128 v[192:195], v161 offset:16384
	ds_read_b128 v[196:199], v161 offset:17408
	ds_read_b128 v[200:203], v161 offset:18432
	ds_read_b128 v[204:207], v161 offset:19456
	ds_read_b128 v[208:211], v161 offset:20480
	ds_read_b128 v[212:215], v161 offset:21504
	ds_read_b128 v[216:219], v161 offset:22528
	ds_read_b128 v[220:223], v161 offset:23552
	s_waitcnt vmcnt(24)
	s_waitcnt lgkmcnt(0)
	s_barrier
	s_setprio 1
	s_waitcnt lgkmcnt(0)
	v_mfma_f32_16x16x32_bf16 v[92:95], v[146:149], v[192:195], 0
	v_mfma_f32_16x16x32_bf16 v[88:91], v[166:169], v[192:195], 0
	v_mfma_f32_16x16x32_bf16 v[84:87], v[146:149], v[200:203], 0
	v_mfma_f32_16x16x32_bf16 v[80:83], v[166:169], v[200:203], 0
	v_mfma_f32_16x16x32_bf16 v[76:79], v[146:149], v[208:211], 0
	v_mfma_f32_16x16x32_bf16 v[72:75], v[166:169], v[208:211], 0
	v_mfma_f32_16x16x32_bf16 v[60:63], v[146:149], v[216:219], 0
	v_mfma_f32_16x16x32_bf16 v[52:55], v[166:169], v[216:219], 0
	v_mfma_f32_16x16x32_bf16 v[92:95], v[162:165], v[196:199], v[92:95]
	v_mfma_f32_16x16x32_bf16 v[88:91], v[170:173], v[196:199], v[88:91]
	v_mfma_f32_16x16x32_bf16 v[84:87], v[162:165], v[204:207], v[84:87]
	v_mfma_f32_16x16x32_bf16 v[80:83], v[170:173], v[204:207], v[80:83]
	v_mfma_f32_16x16x32_bf16 v[76:79], v[162:165], v[212:215], v[76:79]
	v_mfma_f32_16x16x32_bf16 v[72:75], v[170:173], v[212:215], v[72:75]
	v_mfma_f32_16x16x32_bf16 v[60:63], v[162:165], v[220:223], v[60:63]
	v_mfma_f32_16x16x32_bf16 v[52:55], v[170:173], v[220:223], v[52:55]
	s_setprio 0
	s_setprio 1
	v_mfma_f32_16x16x32_bf16 v[28:31], v[176:179], v[192:195], 0
	v_mfma_f32_16x16x32_bf16 v[24:27], v[184:187], v[192:195], 0
	v_mfma_f32_16x16x32_bf16 v[20:23], v[176:179], v[200:203], 0
	v_mfma_f32_16x16x32_bf16 v[16:19], v[184:187], v[200:203], 0
	v_mfma_f32_16x16x32_bf16 v[12:15], v[176:179], v[208:211], 0
	v_mfma_f32_16x16x32_bf16 v[8:11], v[184:187], v[208:211], 0
	v_mfma_f32_16x16x32_bf16 v[4:7], v[176:179], v[216:219], 0
	v_mfma_f32_16x16x32_bf16 v[0:3], v[184:187], v[216:219], 0
	v_mfma_f32_16x16x32_bf16 v[28:31], v[180:183], v[196:199], v[28:31]
	v_mfma_f32_16x16x32_bf16 v[24:27], v[188:191], v[196:199], v[24:27]
	v_mfma_f32_16x16x32_bf16 v[20:23], v[180:183], v[204:207], v[20:23]
	v_mfma_f32_16x16x32_bf16 v[16:19], v[188:191], v[204:207], v[16:19]
	v_mfma_f32_16x16x32_bf16 v[12:15], v[180:183], v[212:215], v[12:15]
	v_mfma_f32_16x16x32_bf16 v[8:11], v[188:191], v[212:215], v[8:11]
	v_mfma_f32_16x16x32_bf16 v[4:7], v[180:183], v[220:223], v[4:7]
	v_mfma_f32_16x16x32_bf16 v[0:3], v[188:191], v[220:223], v[0:3]
	s_setprio 0
	s_barrier
; #define PG8_STAGE(bufoff, gbase, voff) do { _Pragma("unroll") for (int _i = 0; _i < 2; ++_i) \
;         __builtin_amdgcn_global_load_lds((const unsigned*)((const char*)(gbase) + (voff)[_i]), (PG8_LAS unsigned*)(lds + (bufoff) + ldsw + _i * 8192), 16, 0, 0); } while (0)
; #define PG8_LDA(dst, b, h) do { _Pragma("unroll") for (int m = 0; m < 4; ++m) _Pragma("unroll") for (int k = 0; k < 2; ++k) dst[m][k] = *(const PG8_LAS bf16x8*)(lds + PG8_SA(b, h) + aoff + m * 2048 + k * 1024); } while (0)
; #define PG8_LDB(dst, b, h) do { _Pragma("unroll") for (int n = 0; n < 2; ++n) _Pragma("unroll") for (int k = 0; k < 2; ++k) dst[n][k] = *(const PG8_LAS bf16x8*)(lds + PG8_SB(b, h) + boff + n * 2048 + k * 1024); } while (0)
; #define PG8_MMA(ai, bj, At, Bt) do { __builtin_amdgcn_s_setprio(1); _Pragma("unroll") for (int m = 0; m < 4; ++m) _Pragma("unroll") for (int n = 0; n < 2; ++n) _Pragma("unroll") for (int k = 0; k < 2; ++k) \
;         acc[ai][bj][m][n] = __builtin_amdgcn_mfma_f32_16x16x32_bf16(Bt[n][k], At[m][k], acc[ai][bj][m][n], 0, 0, 0); __builtin_amdgcn_s_setprio(0); } while (0)
; #define PG8_WAIT_V(n) asm volatile("s_waitcnt vmcnt(" #n ")" ::: "memory")
; #define PG8_WAIT_L(n) asm volatile("s_waitcnt lgkmcnt(" #n ")" ::: "memory")
; #define PG8_BAR __builtin_amdgcn_s_barrier()
; #define PG8_SCHED __builtin_amdgcn_sched_barrier(0)
; template <class Epi, class Sched, bool ALIGN_EPI = false, bool SP2 = false>
; __device__ __forceinline__ void gemm_phase(PG8_LAS unsigned char* lds, const Gemm g, const Sched& S, const Epi& E) {
;     ...
;             PG8_LDB(B0, 1, 0); PG8_LDB(B1, 1, 1); PG8_SCHED; PG8_LDA(At, 1, 0); PG8_STAGE(PG8_SA(0, 1), a2 + hstepA, voffA);
;             PG8_WAIT_V(8); PG8_WAIT_L(0); PG8_BAR; PG8_MMA(0, 0, At, B0); PG8_MMA(0, 1, At, B1); PG8_BAR; PG8_SCHED;
	s_add_i32 s75, 0, 0x18000
	s_add_i32 s33, 0, 0x1c000
	v_add_u32_e32 v170, s75, v151
	v_add_u32_e32 v175, s33, v151
	s_add_u32 s76, s84, 0x40000
	s_addc_u32 s77, s85, 0
	s_mov_b32 m0, s87
	v_lshl_add_u64 v[232:233], s[76:77], 0, v[134:135]
	global_load_lds_dwordx4 v[232:233], off
	v_lshl_add_u64 v[232:233], s[76:77], 0, v[130:131]
	s_mov_b32 m0, s88
	s_nop 0
	global_load_lds_dwordx4 v[232:233], off
	ds_read_b128 v[146:149], v170
	ds_read_b128 v[162:165], v170 offset:1024
	ds_read_b128 v[166:169], v170 offset:2048
	ds_read_b128 v[170:173], v170 offset:3072
	ds_read_b128 v[176:179], v175
	ds_read_b128 v[180:183], v175 offset:1024
	ds_read_b128 v[184:187], v175 offset:2048
	ds_read_b128 v[188:191], v175 offset:3072
	ds_read_b128 v[192:195], v161 offset:32768
	ds_read_b128 v[196:199], v161 offset:33792
	ds_read_b128 v[200:203], v161 offset:34816
	ds_read_b128 v[204:207], v161 offset:35840
	ds_read_b128 v[208:211], v161 offset:36864
	ds_read_b128 v[212:215], v161 offset:37888
	ds_read_b128 v[216:219], v161 offset:38912
	ds_read_b128 v[220:223], v161 offset:39936
	s_waitcnt vmcnt(24)
	s_waitcnt lgkmcnt(0)
	s_barrier
	s_setprio 1
	s_waitcnt lgkmcnt(0)
	v_mfma_f32_16x16x32_bf16 v[124:127], v[146:149], v[192:195], v[124:127]
	v_mfma_f32_16x16x32_bf16 v[120:123], v[166:169], v[192:195], v[120:123]
	v_mfma_f32_16x16x32_bf16 v[116:119], v[146:149], v[200:203], v[116:119]
	v_mfma_f32_16x16x32_bf16 v[112:115], v[166:169], v[200:203], v[112:115]
	v_mfma_f32_16x16x32_bf16 v[108:111], v[146:149], v[208:211], v[108:111]
	v_mfma_f32_16x16x32_bf16 v[104:107], v[166:169], v[208:211], v[104:107]
	v_mfma_f32_16x16x32_bf16 v[100:103], v[146:149], v[216:219], v[100:103]
	v_mfma_f32_16x16x32_bf16 v[96:99], v[166:169], v[216:219], v[96:99]
	v_mfma_f32_16x16x32_bf16 v[124:127], v[162:165], v[196:199], v[124:127]
	v_mfma_f32_16x16x32_bf16 v[120:123], v[170:173], v[196:199], v[120:123]
	v_mfma_f32_16x16x32_bf16 v[116:119], v[162:165], v[204:207], v[116:119]
	v_mfma_f32_16x16x32_bf16 v[112:115], v[170:173], v[204:207], v[112:115]
	v_mfma_f32_16x16x32_bf16 v[108:111], v[162:165], v[212:215], v[108:111]
	v_mfma_f32_16x16x32_bf16 v[104:107], v[170:173], v[212:215], v[104:107]
	v_mfma_f32_16x16x32_bf16 v[100:103], v[162:165], v[220:223], v[100:103]
	v_mfma_f32_16x16x32_bf16 v[96:99], v[170:173], v[220:223], v[96:99]
	s_setprio 0
	s_setprio 1
	v_mfma_f32_16x16x32_bf16 v[68:71], v[176:179], v[192:195], v[68:71]
	v_mfma_f32_16x16x32_bf16 v[64:67], v[184:187], v[192:195], v[64:67]
	v_mfma_f32_16x16x32_bf16 v[56:59], v[176:179], v[200:203], v[56:59]
	v_mfma_f32_16x16x32_bf16 v[48:51], v[184:187], v[200:203], v[48:51]
	v_mfma_f32_16x16x32_bf16 v[44:47], v[176:179], v[208:211], v[44:47]
	v_mfma_f32_16x16x32_bf16 v[40:43], v[184:187], v[208:211], v[40:43]
	v_mfma_f32_16x16x32_bf16 v[36:39], v[176:179], v[216:219], v[36:39]
	v_mfma_f32_16x16x32_bf16 v[32:35], v[184:187], v[216:219], v[32:35]
	v_mfma_f32_16x16x32_bf16 v[68:71], v[180:183], v[196:199], v[68:71]
	v_mfma_f32_16x16x32_bf16 v[64:67], v[188:191], v[196:199], v[64:67]
	v_mfma_f32_16x16x32_bf16 v[56:59], v[180:183], v[204:207], v[56:59]
	v_mfma_f32_16x16x32_bf16 v[48:51], v[188:191], v[204:207], v[48:51]
	v_mfma_f32_16x16x32_bf16 v[44:47], v[180:183], v[212:215], v[44:47]
	v_mfma_f32_16x16x32_bf16 v[40:43], v[188:191], v[212:215], v[40:43]
	v_mfma_f32_16x16x32_bf16 v[36:39], v[180:183], v[220:223], v[36:39]
	v_mfma_f32_16x16x32_bf16 v[32:35], v[188:191], v[220:223], v[32:35]
	s_setprio 0
	s_barrier
; #define PG8_STAGE(bufoff, gbase, voff) do { _Pragma("unroll") for (int _i = 0; _i < 2; ++_i) \
;         __builtin_amdgcn_global_load_lds((const unsigned*)((const char*)(gbase) + (voff)[_i]), (PG8_LAS unsigned*)(lds + (bufoff) + ldsw + _i * 8192), 16, 0, 0); } while (0)
; #define PG8_LDA(dst, b, h) do { _Pragma("unroll") for (int m = 0; m < 4; ++m) _Pragma("unroll") for (int k = 0; k < 2; ++k) dst[m][k] = *(const PG8_LAS bf16x8*)(lds + PG8_SA(b, h) + aoff + m * 2048 + k * 1024); } while (0)
; #define PG8_MMA(ai, bj, At, Bt) do { __builtin_amdgcn_s_setprio(1); _Pragma("unroll") for (int m = 0; m < 4; ++m) _Pragma("unroll") for (int n = 0; n < 2; ++n) _Pragma("unroll") for (int k = 0; k < 2; ++k) \
;         acc[ai][bj][m][n] = __builtin_amdgcn_mfma_f32_16x16x32_bf16(Bt[n][k], At[m][k], acc[ai][bj][m][n], 0, 0, 0); __builtin_amdgcn_s_setprio(0); } while (0)
; #define PG8_WAIT_V(n) asm volatile("s_waitcnt vmcnt(" #n ")" ::: "memory")
; #define PG8_WAIT_L(n) asm volatile("s_waitcnt lgkmcnt(" #n ")" ::: "memory")
; #define PG8_BAR __builtin_amdgcn_s_barrier()
; #define PG8_SCHED __builtin_amdgcn_sched_barrier(0)
; template <class Epi, class Sched, bool ALIGN_EPI = false, bool SP2 = false>
; __device__ __forceinline__ void gemm_phase(PG8_LAS unsigned char* lds, const Gemm g, const Sched& S, const Epi& E) {
;     ...
;             PG8_LDA(At, 1, 1); PG8_STAGE(PG8_SB(1, 0), b3, voffB); PG8_STAGE(PG8_SB(1, 1), b3 + hstepB, voffB); PG8_STAGE(PG8_SA(1, 0), a3, voffA);
;             PG8_WAIT_V(8); PG8_WAIT_L(0); PG8_BAR; PG8_MMA(1, 0, At, B0); PG8_MMA(1, 1, At, B1); PG8_BAR; PG8_SCHED;
	s_add_i32 s75, s75, s27
	v_lshl_add_u64 v[224:225], v[224:225], 0, s[8:9]
	s_mov_b32 m0, s75
	s_nop 0
	global_load_lds_dwordx4 v[224:225], off
	s_add_i32 m0, s75, 0x2000
	s_add_u32 s66, s66, 0x40080
	v_lshl_add_u64 v[224:225], v[226:227], 0, s[8:9]
	s_addc_u32 s67, s67, 0
	s_add_i32 s33, s33, s27
	global_load_lds_dwordx4 v[224:225], off
	v_lshl_add_u64 v[224:225], s[66:67], 0, v[132:133]
	s_mov_b32 m0, s33
	s_nop 0
	global_load_lds_dwordx4 v[224:225], off
	v_lshl_add_u64 v[224:225], s[66:67], 0, v[128:129]
	s_add_i32 m0, s33, 0x2000
	s_nop 0
	global_load_lds_dwordx4 v[224:225], off
	v_lshl_add_u64 v[224:225], v[228:229], 0, s[8:9]
	s_mov_b32 m0, s91
	s_nop 0
	global_load_lds_dwordx4 v[224:225], off
	v_lshl_add_u64 v[224:225], v[230:231], 0, s[8:9]
	s_mov_b32 m0, s92
	s_nop 0
	global_load_lds_dwordx4 v[224:225], off
	ds_read_b128 v[192:195], v161 offset:49152
	ds_read_b128 v[196:199], v161 offset:50176
	ds_read_b128 v[200:203], v161 offset:51200
	ds_read_b128 v[204:207], v161 offset:52224
	ds_read_b128 v[208:211], v161 offset:53248
	ds_read_b128 v[212:215], v161 offset:54272
	ds_read_b128 v[216:219], v161 offset:55296
	ds_read_b128 v[220:223], v161 offset:56320
	s_waitcnt vmcnt(8)
	s_waitcnt lgkmcnt(0)
	s_barrier
	s_setprio 1
	s_waitcnt lgkmcnt(0)
	v_mfma_f32_16x16x32_bf16 v[92:95], v[146:149], v[192:195], v[92:95]
	v_mfma_f32_16x16x32_bf16 v[88:91], v[166:169], v[192:195], v[88:91]
	v_mfma_f32_16x16x32_bf16 v[84:87], v[146:149], v[200:203], v[84:87]
	v_mfma_f32_16x16x32_bf16 v[80:83], v[166:169], v[200:203], v[80:83]
	v_mfma_f32_16x16x32_bf16 v[76:79], v[146:149], v[208:211], v[76:79]
	v_mfma_f32_16x16x32_bf16 v[72:75], v[166:169], v[208:211], v[72:75]
	v_mfma_f32_16x16x32_bf16 v[60:63], v[146:149], v[216:219], v[60:63]
	v_mfma_f32_16x16x32_bf16 v[52:55], v[166:169], v[216:219], v[52:55]
	v_mfma_f32_16x16x32_bf16 v[92:95], v[162:165], v[196:199], v[92:95]
	v_mfma_f32_16x16x32_bf16 v[88:91], v[170:173], v[196:199], v[88:91]
	v_mfma_f32_16x16x32_bf16 v[84:87], v[162:165], v[204:207], v[84:87]
	v_mfma_f32_16x16x32_bf16 v[80:83], v[170:173], v[204:207], v[80:83]
	v_mfma_f32_16x16x32_bf16 v[76:79], v[162:165], v[212:215], v[76:79]
	v_mfma_f32_16x16x32_bf16 v[72:75], v[170:173], v[212:215], v[72:75]
	v_mfma_f32_16x16x32_bf16 v[60:63], v[162:165], v[220:223], v[60:63]
	v_mfma_f32_16x16x32_bf16 v[52:55], v[170:173], v[220:223], v[52:55]
	s_setprio 0
	s_setprio 1
	v_mfma_f32_16x16x32_bf16 v[28:31], v[176:179], v[192:195], v[28:31]
	v_mfma_f32_16x16x32_bf16 v[24:27], v[184:187], v[192:195], v[24:27]
	v_mfma_f32_16x16x32_bf16 v[20:23], v[176:179], v[200:203], v[20:23]
	v_mfma_f32_16x16x32_bf16 v[16:19], v[184:187], v[200:203], v[16:19]
	v_mfma_f32_16x16x32_bf16 v[12:15], v[176:179], v[208:211], v[12:15]
	v_mfma_f32_16x16x32_bf16 v[8:11], v[184:187], v[208:211], v[8:11]
	v_mfma_f32_16x16x32_bf16 v[4:7], v[176:179], v[216:219], v[4:7]
	v_mfma_f32_16x16x32_bf16 v[0:3], v[184:187], v[216:219], v[0:3]
	v_mfma_f32_16x16x32_bf16 v[28:31], v[180:183], v[196:199], v[28:31]
	v_mfma_f32_16x16x32_bf16 v[24:27], v[188:191], v[196:199], v[24:27]
	v_mfma_f32_16x16x32_bf16 v[20:23], v[180:183], v[204:207], v[20:23]
	v_mfma_f32_16x16x32_bf16 v[16:19], v[188:191], v[204:207], v[16:19]
	v_mfma_f32_16x16x32_bf16 v[12:15], v[180:183], v[212:215], v[12:15]
	v_mfma_f32_16x16x32_bf16 v[8:11], v[188:191], v[212:215], v[8:11]
	v_mfma_f32_16x16x32_bf16 v[4:7], v[180:183], v[220:223], v[4:7]
	v_mfma_f32_16x16x32_bf16 v[0:3], v[188:191], v[220:223], v[0:3]
	s_setprio 0
	s_barrier
	s_add_i32 s74, s74, 2
	s_add_u32 s60, s60, 0x100
	s_addc_u32 s61, s61, 0
	s_add_u32 s80, s80, 0x100
	s_addc_u32 s81, s81, 0
	s_cmp_gt_u32 s74, 13
	s_branch .LBB0_197

; #define PG8_STAGE(bufoff, gbase, voff) do { _Pragma("unroll") for (int _i = 0; _i < 2; ++_i) \
;         __builtin_amdgcn_global_load_lds((const unsigned*)((const char*)(gbase) + (voff)[_i]), (PG8_LAS unsigned*)(lds + (bufoff) + ldsw + _i * 8192), 16, 0, 0); } while (0)
; #define PG8_LDA(dst, b, h) do { _Pragma("unroll") for (int m = 0; m < 4; ++m) _Pragma("unroll") for (int k = 0; k < 2; ++k) dst[m][k] = *(const PG8_LAS bf16x8*)(lds + PG8_SA(b, h) + aoff + m * 2048 + k * 1024); } while (0)
; #define PG8_LDB(dst, b, h) do { _Pragma("unroll") for (int n = 0; n < 2; ++n) _Pragma("unroll") for (int k = 0; k < 2; ++k) dst[n][k] = *(const PG8_LAS bf16x8*)(lds + PG8_SB(b, h) + boff + n * 2048 + k * 1024); } while (0)
; #define PG8_MMA(ai, bj, At, Bt) do { __builtin_amdgcn_s_setprio(1); _Pragma("unroll") for (int m = 0; m < 4; ++m) _Pragma("unroll") for (int n = 0; n < 2; ++n) _Pragma("unroll") for (int k = 0; k < 2; ++k) \
;         acc[ai][bj][m][n] = __builtin_amdgcn_mfma_f32_16x16x32_bf16(Bt[n][k], At[m][k], acc[ai][bj][m][n], 0, 0, 0); __builtin_amdgcn_s_setprio(0); } while (0)
; #define PG8_WAIT_V(n) asm volatile("s_waitcnt vmcnt(" #n ")" ::: "memory")
; template <class Epi, class Sched, bool ALIGN_EPI = false, bool SP2 = false>
; __device__ __forceinline__ void gemm_phase(PG8_LAS unsigned char* lds, const Gemm g, const Sched& S, const Epi& E) {
;     ...
;             PG8_LDB(B0, 0, 0); PG8_LDB(B1, 0, 1); PG8_SCHED; PG8_LDA(At, 0, 0); PG8_STAGE(PG8_SA(1, 1), a1 + hstepA, voffA);
;             PG8_WAIT_V(8); PG8_WAIT_L(0); PG8_BAR; PG8_MMA(0, 0, At, B0); PG8_MMA(0, 1, At, B1); PG8_BAR; PG8_SCHED;
;             PG8_LDA(At, 0, 1); PG8_STAGE(PG8_SB(0, 0), b2, voffB); PG8_STAGE(PG8_SB(0, 1), b2 + hstepB, voffB); PG8_STAGE(PG8_SA(0, 0), a2, voffA);
;             PG8_WAIT_V(8); PG8_WAIT_L(0); PG8_BAR; PG8_MMA(1, 0, At, B0); PG8_MMA(1, 1, At, B1); PG8_BAR; PG8_SCHED;
;             PG8_LDB(B0, 1, 0); PG8_LDB(B1, 1, 1); PG8_SCHED; PG8_LDA(At, 1, 0); PG8_STAGE(PG8_SA(0, 1), a2 + hstepA, voffA);
;             PG8_WAIT_V(8); PG8_WAIT_L(0); PG8_BAR; PG8_MMA(0, 0, At, B0); PG8_MMA(0, 1, At, B1); PG8_BAR; PG8_SCHED;
;             PG8_LDA(At, 1, 1); PG8_STAGE(PG8_SB(1, 0), b3, voffB); PG8_STAGE(PG8_SB(1, 1), b3 + hstepB, voffB); PG8_STAGE(PG8_SA(1, 0), a3, voffA);
;             PG8_WAIT_V(8); PG8_WAIT_L(0); PG8_BAR; PG8_MMA(1, 0, At, B0); PG8_MMA(1, 1, At, B1); PG8_BAR; PG8_SCHED;
.LBB0_482:
	s_add_u32 s33, s50, 0xfffc0080
	s_addc_u32 s52, s51, -1
	s_cmp_eq_u32 s74, 12
	s_cselect_b32 s55, s43, s52
	s_cselect_b32 s54, s82, s33
	s_cselect_b32 s53, s41, s85
	s_cselect_b32 s52, s83, s84
	v_lshl_add_u64 v[164:165], s[50:51], 0, v[152:153]
	s_add_i32 m0, s30, 0xc000
	s_nop 0
	global_load_lds_dwordx4 v[164:165], off
	v_lshl_add_u64 v[164:165], s[50:51], 0, v[154:155]
	s_add_i32 m0, s30, 0xe000
	s_nop 0
	global_load_lds_dwordx4 v[164:165], off
	ds_read_b128 v[128:131], v169
	ds_read_b128 v[132:135], v169 offset:1024
	ds_read_b128 v[136:139], v169 offset:2048
	ds_read_b128 v[140:143], v169 offset:3072
	ds_read_b128 v[160:163], v170
	ds_read_b128 v[176:179], v170 offset:1024
	ds_read_b128 v[180:183], v170 offset:2048
	ds_read_b128 v[184:187], v170 offset:3072
	ds_read_b128 v[188:191], v171
	ds_read_b128 v[192:195], v171 offset:1024
	ds_read_b128 v[196:199], v171 offset:2048
	ds_read_b128 v[200:203], v171 offset:3072
	ds_read_b128 v[204:207], v171 offset:4096
	ds_read_b128 v[208:211], v171 offset:5120
	ds_read_b128 v[212:215], v171 offset:6144
	ds_read_b128 v[216:219], v171 offset:7168
	s_waitcnt vmcnt(8)
	s_waitcnt lgkmcnt(0)
	s_barrier
	s_setprio 1
	s_waitcnt lgkmcnt(0)
	v_mfma_f32_16x16x32_bf16 v[124:127], v[128:131], v[188:191], v[124:127]
	v_mfma_f32_16x16x32_bf16 v[120:123], v[136:139], v[188:191], v[120:123]
	v_mfma_f32_16x16x32_bf16 v[116:119], v[128:131], v[196:199], v[116:119]
	v_mfma_f32_16x16x32_bf16 v[112:115], v[136:139], v[196:199], v[112:115]
	v_mfma_f32_16x16x32_bf16 v[108:111], v[128:131], v[204:207], v[108:111]
	v_mfma_f32_16x16x32_bf16 v[104:107], v[136:139], v[204:207], v[104:107]
	v_mfma_f32_16x16x32_bf16 v[100:103], v[128:131], v[212:215], v[100:103]
	v_mfma_f32_16x16x32_bf16 v[96:99], v[136:139], v[212:215], v[96:99]
	v_mfma_f32_16x16x32_bf16 v[124:127], v[132:135], v[192:195], v[124:127]
	v_mfma_f32_16x16x32_bf16 v[120:123], v[140:143], v[192:195], v[120:123]
	v_mfma_f32_16x16x32_bf16 v[116:119], v[132:135], v[200:203], v[116:119]
	v_mfma_f32_16x16x32_bf16 v[112:115], v[140:143], v[200:203], v[112:115]
	v_mfma_f32_16x16x32_bf16 v[108:111], v[132:135], v[208:211], v[108:111]
	v_mfma_f32_16x16x32_bf16 v[104:107], v[140:143], v[208:211], v[104:107]
	v_mfma_f32_16x16x32_bf16 v[100:103], v[132:135], v[216:219], v[100:103]
	v_mfma_f32_16x16x32_bf16 v[96:99], v[140:143], v[216:219], v[96:99]
	s_setprio 0
	s_setprio 1
	v_mfma_f32_16x16x32_bf16 v[68:71], v[160:163], v[188:191], v[68:71]
	v_mfma_f32_16x16x32_bf16 v[64:67], v[180:183], v[188:191], v[64:67]
	v_mfma_f32_16x16x32_bf16 v[52:55], v[160:163], v[196:199], v[52:55]
	v_mfma_f32_16x16x32_bf16 v[48:51], v[180:183], v[196:199], v[48:51]
	v_mfma_f32_16x16x32_bf16 v[44:47], v[160:163], v[204:207], v[44:47]
	v_mfma_f32_16x16x32_bf16 v[40:43], v[180:183], v[204:207], v[40:43]
	v_mfma_f32_16x16x32_bf16 v[36:39], v[160:163], v[212:215], v[36:39]
	v_mfma_f32_16x16x32_bf16 v[32:35], v[180:183], v[212:215], v[32:35]
	v_mfma_f32_16x16x32_bf16 v[68:71], v[176:179], v[192:195], v[68:71]
	v_mfma_f32_16x16x32_bf16 v[64:67], v[184:187], v[192:195], v[64:67]
	v_mfma_f32_16x16x32_bf16 v[52:55], v[176:179], v[200:203], v[52:55]
	v_mfma_f32_16x16x32_bf16 v[48:51], v[184:187], v[200:203], v[48:51]
	v_mfma_f32_16x16x32_bf16 v[44:47], v[176:179], v[208:211], v[44:47]
	v_mfma_f32_16x16x32_bf16 v[40:43], v[184:187], v[208:211], v[40:43]
	v_mfma_f32_16x16x32_bf16 v[36:39], v[176:179], v[216:219], v[36:39]
	v_mfma_f32_16x16x32_bf16 v[32:35], v[184:187], v[216:219], v[32:35]
	s_setprio 0
	s_barrier
	s_add_i32 s33, s61, s23
	v_lshl_add_u64 v[164:165], s[52:53], 0, v[146:147]
	s_mov_b32 m0, s33
	s_nop 0
	global_load_lds_dwordx4 v[164:165], off
	s_add_i32 m0, s33, 0x2000
	s_add_u32 s76, s52, 0x40000
	v_lshl_add_u64 v[172:173], s[52:53], 0, v[150:151]
	s_addc_u32 s77, s53, 0
	s_add_i32 s33, s66, s23
	global_load_lds_dwordx4 v[172:173], off
	v_lshl_add_u64 v[220:221], s[76:77], 0, v[146:147]
	s_mov_b32 m0, s33
	v_lshl_add_u64 v[222:223], s[54:55], 0, v[148:149]
	global_load_lds_dwordx4 v[220:221], off
	v_lshl_add_u64 v[220:221], s[76:77], 0, v[150:151]
	s_add_i32 m0, s33, 0x2000
	s_nop 0
	global_load_lds_dwordx4 v[220:221], off
	v_lshl_add_u64 v[220:221], s[54:55], 0, v[144:145]
	s_mov_b32 m0, s30
	s_nop 0
	global_load_lds_dwordx4 v[220:221], off
	s_mov_b32 m0, s31
	s_nop 0
	global_load_lds_dwordx4 v[222:223], off
	ds_read_b128 v[188:191], v171 offset:16384
	ds_read_b128 v[192:195], v171 offset:17408
	ds_read_b128 v[196:199], v171 offset:18432
	ds_read_b128 v[200:203], v171 offset:19456
	ds_read_b128 v[204:207], v171 offset:20480
	ds_read_b128 v[208:211], v171 offset:21504
	ds_read_b128 v[212:215], v171 offset:22528
	ds_read_b128 v[216:219], v171 offset:23552
	s_waitcnt vmcnt(8)
	s_waitcnt lgkmcnt(0)
	s_barrier
; #define PG8_STAGE(bufoff, gbase, voff) do { _Pragma("unroll") for (int _i = 0; _i < 2; ++_i) \
;         __builtin_amdgcn_global_load_lds((const unsigned*)((const char*)(gbase) + (voff)[_i]), (PG8_LAS unsigned*)(lds + (bufoff) + ldsw + _i * 8192), 16, 0, 0); } while (0)
; #define PG8_LDA(dst, b, h) do { _Pragma("unroll") for (int m = 0; m < 4; ++m) _Pragma("unroll") for (int k = 0; k < 2; ++k) dst[m][k] = *(const PG8_LAS bf16x8*)(lds + PG8_SA(b, h) + aoff + m * 2048 + k * 1024); } while (0)
; #define PG8_LDB(dst, b, h) do { _Pragma("unroll") for (int n = 0; n < 2; ++n) _Pragma("unroll") for (int k = 0; k < 2; ++k) dst[n][k] = *(const PG8_LAS bf16x8*)(lds + PG8_SB(b, h) + boff + n * 2048 + k * 1024); } while (0)
; #define PG8_MMA(ai, bj, At, Bt) do { __builtin_amdgcn_s_setprio(1); _Pragma("unroll") for (int m = 0; m < 4; ++m) _Pragma("unroll") for (int n = 0; n < 2; ++n) _Pragma("unroll") for (int k = 0; k < 2; ++k) \
;         acc[ai][bj][m][n] = __builtin_amdgcn_mfma_f32_16x16x32_bf16(Bt[n][k], At[m][k], acc[ai][bj][m][n], 0, 0, 0); __builtin_amdgcn_s_setprio(0); } while (0)
; #define PG8_WAIT_V(n) asm volatile("s_waitcnt vmcnt(" #n ")" ::: "memory")
; template <class Epi, class Sched, bool ALIGN_EPI = false, bool SP2 = false>
; __device__ __forceinline__ void gemm_phase(PG8_LAS unsigned char* lds, const Gemm g, const Sched& S, const Epi& E) {
;     ...
;             PG8_LDB(B0, 0, 0); PG8_LDB(B1, 0, 1); PG8_SCHED; PG8_LDA(At, 0, 0); PG8_STAGE(PG8_SA(1, 1), a1 + hstepA, voffA);
;             PG8_WAIT_V(8); PG8_WAIT_L(0); PG8_BAR; PG8_MMA(0, 0, At, B0); PG8_MMA(0, 1, At, B1); PG8_BAR; PG8_SCHED;
;             PG8_LDA(At, 0, 1); PG8_STAGE(PG8_SB(0, 0), b2, voffB); PG8_STAGE(PG8_SB(0, 1), b2 + hstepB, voffB); PG8_STAGE(PG8_SA(0, 0), a2, voffA);
;             PG8_WAIT_V(8); PG8_WAIT_L(0); PG8_BAR; PG8_MMA(1, 0, At, B0); PG8_MMA(1, 1, At, B1); PG8_BAR; PG8_SCHED;
;             PG8_LDB(B0, 1, 0); PG8_LDB(B1, 1, 1); PG8_SCHED; PG8_LDA(At, 1, 0); PG8_STAGE(PG8_SA(0, 1), a2 + hstepA, voffA);
;             PG8_WAIT_V(8); PG8_WAIT_L(0); PG8_BAR; PG8_MMA(0, 0, At, B0); PG8_MMA(0, 1, At, B1); PG8_BAR; PG8_SCHED;
;             PG8_LDA(At, 1, 1); PG8_STAGE(PG8_SB(1, 0), b3, voffB); PG8_STAGE(PG8_SB(1, 1), b3 + hstepB, voffB); PG8_STAGE(PG8_SA(1, 0), a3, voffA);
;             PG8_WAIT_V(8); PG8_WAIT_L(0); PG8_BAR; PG8_MMA(1, 0, At, B0); PG8_MMA(1, 1, At, B1); PG8_BAR; PG8_SCHED;
	s_setprio 1
	s_waitcnt lgkmcnt(0)
	v_mfma_f32_16x16x32_bf16 v[92:95], v[128:131], v[188:191], v[92:95]
	v_mfma_f32_16x16x32_bf16 v[88:91], v[136:139], v[188:191], v[88:91]
	v_mfma_f32_16x16x32_bf16 v[84:87], v[128:131], v[196:199], v[84:87]
	v_mfma_f32_16x16x32_bf16 v[80:83], v[136:139], v[196:199], v[80:83]
	v_mfma_f32_16x16x32_bf16 v[76:79], v[128:131], v[204:207], v[76:79]
	v_mfma_f32_16x16x32_bf16 v[72:75], v[136:139], v[204:207], v[72:75]
	v_mfma_f32_16x16x32_bf16 v[60:63], v[128:131], v[212:215], v[60:63]
	v_mfma_f32_16x16x32_bf16 v[56:59], v[136:139], v[212:215], v[56:59]
	v_mfma_f32_16x16x32_bf16 v[92:95], v[132:135], v[192:195], v[92:95]
	v_mfma_f32_16x16x32_bf16 v[88:91], v[140:143], v[192:195], v[88:91]
	v_mfma_f32_16x16x32_bf16 v[84:87], v[132:135], v[200:203], v[84:87]
	v_mfma_f32_16x16x32_bf16 v[80:83], v[140:143], v[200:203], v[80:83]
	v_mfma_f32_16x16x32_bf16 v[76:79], v[132:135], v[208:211], v[76:79]
	v_mfma_f32_16x16x32_bf16 v[72:75], v[140:143], v[208:211], v[72:75]
	v_mfma_f32_16x16x32_bf16 v[60:63], v[132:135], v[216:219], v[60:63]
	v_mfma_f32_16x16x32_bf16 v[56:59], v[140:143], v[216:219], v[56:59]
	s_setprio 0
	s_setprio 1
	v_mfma_f32_16x16x32_bf16 v[28:31], v[160:163], v[188:191], v[28:31]
	v_mfma_f32_16x16x32_bf16 v[24:27], v[180:183], v[188:191], v[24:27]
	v_mfma_f32_16x16x32_bf16 v[20:23], v[160:163], v[196:199], v[20:23]
	v_mfma_f32_16x16x32_bf16 v[16:19], v[180:183], v[196:199], v[16:19]
	v_mfma_f32_16x16x32_bf16 v[12:15], v[160:163], v[204:207], v[12:15]
	v_mfma_f32_16x16x32_bf16 v[8:11], v[180:183], v[204:207], v[8:11]
	v_mfma_f32_16x16x32_bf16 v[4:7], v[160:163], v[212:215], v[4:7]
	v_mfma_f32_16x16x32_bf16 v[0:3], v[180:183], v[212:215], v[0:3]
	v_mfma_f32_16x16x32_bf16 v[28:31], v[176:179], v[192:195], v[28:31]
	v_mfma_f32_16x16x32_bf16 v[24:27], v[184:187], v[192:195], v[24:27]
	v_mfma_f32_16x16x32_bf16 v[20:23], v[176:179], v[200:203], v[20:23]
	v_mfma_f32_16x16x32_bf16 v[16:19], v[184:187], v[200:203], v[16:19]
	v_mfma_f32_16x16x32_bf16 v[12:15], v[176:179], v[208:211], v[12:15]
	v_mfma_f32_16x16x32_bf16 v[8:11], v[184:187], v[208:211], v[8:11]
	v_mfma_f32_16x16x32_bf16 v[4:7], v[176:179], v[216:219], v[4:7]
	v_mfma_f32_16x16x32_bf16 v[0:3], v[184:187], v[216:219], v[0:3]
	s_setprio 0
	s_barrier
	s_add_i32 s33, 0, 0x18000
	s_add_i32 s75, 0, 0x1c000
	v_add_u32_e32 v140, s33, v167
	v_add_u32_e32 v175, s75, v167
	s_add_u32 s54, s54, 0x40000
	s_addc_u32 s55, s55, 0
	s_mov_b32 m0, s35
	v_lshl_add_u64 v[224:225], s[54:55], 0, v[144:145]
	global_load_lds_dwordx4 v[224:225], off
	v_lshl_add_u64 v[224:225], s[54:55], 0, v[148:149]
	s_mov_b32 m0, s38
	s_nop 0
	global_load_lds_dwordx4 v[224:225], off
	ds_read_b128 v[128:131], v140
	ds_read_b128 v[132:135], v140 offset:1024
	ds_read_b128 v[136:139], v140 offset:2048
	ds_read_b128 v[140:143], v140 offset:3072
	ds_read_b128 v[160:163], v175
	ds_read_b128 v[176:179], v175 offset:1024
	ds_read_b128 v[180:183], v175 offset:2048
	ds_read_b128 v[184:187], v175 offset:3072
	ds_read_b128 v[188:191], v171 offset:32768
	ds_read_b128 v[192:195], v171 offset:33792
	ds_read_b128 v[196:199], v171 offset:34816
	ds_read_b128 v[200:203], v171 offset:35840
	ds_read_b128 v[204:207], v171 offset:36864
	ds_read_b128 v[208:211], v171 offset:37888
	ds_read_b128 v[212:215], v171 offset:38912
	ds_read_b128 v[216:219], v171 offset:39936
	s_waitcnt vmcnt(8)
	s_waitcnt lgkmcnt(0)
	s_barrier
	s_setprio 1
	s_waitcnt lgkmcnt(0)
	v_mfma_f32_16x16x32_bf16 v[124:127], v[128:131], v[188:191], v[124:127]
	v_mfma_f32_16x16x32_bf16 v[120:123], v[136:139], v[188:191], v[120:123]
	v_mfma_f32_16x16x32_bf16 v[116:119], v[128:131], v[196:199], v[116:119]
	v_mfma_f32_16x16x32_bf16 v[112:115], v[136:139], v[196:199], v[112:115]
	v_mfma_f32_16x16x32_bf16 v[108:111], v[128:131], v[204:207], v[108:111]
	v_mfma_f32_16x16x32_bf16 v[104:107], v[136:139], v[204:207], v[104:107]
	v_mfma_f32_16x16x32_bf16 v[100:103], v[128:131], v[212:215], v[100:103]
	v_mfma_f32_16x16x32_bf16 v[96:99], v[136:139], v[212:215], v[96:99]
	v_mfma_f32_16x16x32_bf16 v[124:127], v[132:135], v[192:195], v[124:127]
	v_mfma_f32_16x16x32_bf16 v[120:123], v[140:143], v[192:195], v[120:123]
	v_mfma_f32_16x16x32_bf16 v[116:119], v[132:135], v[200:203], v[116:119]
	v_mfma_f32_16x16x32_bf16 v[112:115], v[140:143], v[200:203], v[112:115]
	v_mfma_f32_16x16x32_bf16 v[108:111], v[132:135], v[208:211], v[108:111]
	v_mfma_f32_16x16x32_bf16 v[104:107], v[140:143], v[208:211], v[104:107]
	v_mfma_f32_16x16x32_bf16 v[100:103], v[132:135], v[216:219], v[100:103]
	v_mfma_f32_16x16x32_bf16 v[96:99], v[140:143], v[216:219], v[96:99]
	s_setprio 0
	s_setprio 1
	v_mfma_f32_16x16x32_bf16 v[68:71], v[160:163], v[188:191], v[68:71]
	v_mfma_f32_16x16x32_bf16 v[64:67], v[180:183], v[188:191], v[64:67]
	v_mfma_f32_16x16x32_bf16 v[52:55], v[160:163], v[196:199], v[52:55]
	v_mfma_f32_16x16x32_bf16 v[48:51], v[180:183], v[196:199], v[48:51]
	v_mfma_f32_16x16x32_bf16 v[44:47], v[160:163], v[204:207], v[44:47]
	v_mfma_f32_16x16x32_bf16 v[40:43], v[180:183], v[204:207], v[40:43]
	v_mfma_f32_16x16x32_bf16 v[36:39], v[160:163], v[212:215], v[36:39]
	v_mfma_f32_16x16x32_bf16 v[32:35], v[180:183], v[212:215], v[32:35]
	v_mfma_f32_16x16x32_bf16 v[68:71], v[176:179], v[192:195], v[68:71]
	v_mfma_f32_16x16x32_bf16 v[64:67], v[184:187], v[192:195], v[64:67]
	v_mfma_f32_16x16x32_bf16 v[52:55], v[176:179], v[200:203], v[52:55]
	v_mfma_f32_16x16x32_bf16 v[48:51], v[184:187], v[200:203], v[48:51]
	v_mfma_f32_16x16x32_bf16 v[44:47], v[176:179], v[208:211], v[44:47]
	v_mfma_f32_16x16x32_bf16 v[40:43], v[184:187], v[208:211], v[40:43]
	v_mfma_f32_16x16x32_bf16 v[36:39], v[176:179], v[216:219], v[36:39]
	v_mfma_f32_16x16x32_bf16 v[32:35], v[184:187], v[216:219], v[32:35]
	s_setprio 0
	s_barrier
; #define PG8_STAGE(bufoff, gbase, voff) do { _Pragma("unroll") for (int _i = 0; _i < 2; ++_i) \
;         __builtin_amdgcn_global_load_lds((const unsigned*)((const char*)(gbase) + (voff)[_i]), (PG8_LAS unsigned*)(lds + (bufoff) + ldsw + _i * 8192), 16, 0, 0); } while (0)
; #define PG8_LDA(dst, b, h) do { _Pragma("unroll") for (int m = 0; m < 4; ++m) _Pragma("unroll") for (int k = 0; k < 2; ++k) dst[m][k] = *(const PG8_LAS bf16x8*)(lds + PG8_SA(b, h) + aoff + m * 2048 + k * 1024); } while (0)
; #define PG8_LDB(dst, b, h) do { _Pragma("unroll") for (int n = 0; n < 2; ++n) _Pragma("unroll") for (int k = 0; k < 2; ++k) dst[n][k] = *(const PG8_LAS bf16x8*)(lds + PG8_SB(b, h) + boff + n * 2048 + k * 1024); } while (0)
; #define PG8_MMA(ai, bj, At, Bt) do { __builtin_amdgcn_s_setprio(1); _Pragma("unroll") for (int m = 0; m < 4; ++m) _Pragma("unroll") for (int n = 0; n < 2; ++n) _Pragma("unroll") for (int k = 0; k < 2; ++k) \
;         acc[ai][bj][m][n] = __builtin_amdgcn_mfma_f32_16x16x32_bf16(Bt[n][k], At[m][k], acc[ai][bj][m][n], 0, 0, 0); __builtin_amdgcn_s_setprio(0); } while (0)
; #define PG8_WAIT_V(n) asm volatile("s_waitcnt vmcnt(" #n ")" ::: "memory")
; template <class Epi, class Sched, bool ALIGN_EPI = false, bool SP2 = false>
; __device__ __forceinline__ void gemm_phase(PG8_LAS unsigned char* lds, const Gemm g, const Sched& S, const Epi& E) {
;     ...
;             PG8_LDB(B0, 0, 0); PG8_LDB(B1, 0, 1); PG8_SCHED; PG8_LDA(At, 0, 0); PG8_STAGE(PG8_SA(1, 1), a1 + hstepA, voffA);
;             PG8_WAIT_V(8); PG8_WAIT_L(0); PG8_BAR; PG8_MMA(0, 0, At, B0); PG8_MMA(0, 1, At, B1); PG8_BAR; PG8_SCHED;
;             PG8_LDA(At, 0, 1); PG8_STAGE(PG8_SB(0, 0), b2, voffB); PG8_STAGE(PG8_SB(0, 1), b2 + hstepB, voffB); PG8_STAGE(PG8_SA(0, 0), a2, voffA);
;             PG8_WAIT_V(8); PG8_WAIT_L(0); PG8_BAR; PG8_MMA(1, 0, At, B0); PG8_MMA(1, 1, At, B1); PG8_BAR; PG8_SCHED;
;             PG8_LDB(B0, 1, 0); PG8_LDB(B1, 1, 1); PG8_SCHED; PG8_LDA(At, 1, 0); PG8_STAGE(PG8_SA(0, 1), a2 + hstepA, voffA);
;             PG8_WAIT_V(8); PG8_WAIT_L(0); PG8_BAR; PG8_MMA(0, 0, At, B0); PG8_MMA(0, 1, At, B1); PG8_BAR; PG8_SCHED;
;             PG8_LDA(At, 1, 1); PG8_STAGE(PG8_SB(1, 0), b3, voffB); PG8_STAGE(PG8_SB(1, 1), b3 + hstepB, voffB); PG8_STAGE(PG8_SA(1, 0), a3, voffA);
;             PG8_WAIT_V(8); PG8_WAIT_L(0); PG8_BAR; PG8_MMA(1, 0, At, B0); PG8_MMA(1, 1, At, B1); PG8_BAR; PG8_SCHED;
	s_add_i32 s33, s33, s23
	v_lshl_add_u64 v[164:165], v[164:165], 0, s[8:9]
	s_mov_b32 m0, s33
	s_nop 0
	global_load_lds_dwordx4 v[164:165], off
	s_add_i32 m0, s33, 0x2000
	s_add_u32 s52, s52, 0x40080
	v_lshl_add_u64 v[164:165], v[172:173], 0, s[8:9]
	s_addc_u32 s53, s53, 0
	s_add_i32 s33, s75, s23
	global_load_lds_dwordx4 v[164:165], off
	v_lshl_add_u64 v[164:165], s[52:53], 0, v[146:147]
	s_mov_b32 m0, s33
	s_nop 0
	global_load_lds_dwordx4 v[164:165], off
	v_lshl_add_u64 v[164:165], s[52:53], 0, v[150:151]
	s_add_i32 m0, s33, 0x2000
	s_nop 0
	global_load_lds_dwordx4 v[164:165], off
	v_lshl_add_u64 v[164:165], v[220:221], 0, s[8:9]
	s_mov_b32 m0, s57
	s_nop 0
	global_load_lds_dwordx4 v[164:165], off
	v_lshl_add_u64 v[164:165], v[222:223], 0, s[8:9]
	s_mov_b32 m0, s58
	s_nop 0
	global_load_lds_dwordx4 v[164:165], off
	ds_read_b128 v[188:191], v171 offset:49152
	ds_read_b128 v[192:195], v171 offset:50176
	ds_read_b128 v[196:199], v171 offset:51200
	ds_read_b128 v[200:203], v171 offset:52224
	ds_read_b128 v[204:207], v171 offset:53248
	ds_read_b128 v[208:211], v171 offset:54272
	ds_read_b128 v[212:215], v171 offset:55296
	ds_read_b128 v[216:219], v171 offset:56320
	s_waitcnt vmcnt(8)
	s_waitcnt lgkmcnt(0)
	s_barrier
	s_setprio 1
	s_waitcnt lgkmcnt(0)
	v_mfma_f32_16x16x32_bf16 v[92:95], v[128:131], v[188:191], v[92:95]
	v_mfma_f32_16x16x32_bf16 v[88:91], v[136:139], v[188:191], v[88:91]
	v_mfma_f32_16x16x32_bf16 v[84:87], v[128:131], v[196:199], v[84:87]
	v_mfma_f32_16x16x32_bf16 v[80:83], v[136:139], v[196:199], v[80:83]
	v_mfma_f32_16x16x32_bf16 v[76:79], v[128:131], v[204:207], v[76:79]
	v_mfma_f32_16x16x32_bf16 v[72:75], v[136:139], v[204:207], v[72:75]
	v_mfma_f32_16x16x32_bf16 v[60:63], v[128:131], v[212:215], v[60:63]
	v_mfma_f32_16x16x32_bf16 v[56:59], v[136:139], v[212:215], v[56:59]
	v_mfma_f32_16x16x32_bf16 v[92:95], v[132:135], v[192:195], v[92:95]
	v_mfma_f32_16x16x32_bf16 v[88:91], v[140:143], v[192:195], v[88:91]
	v_mfma_f32_16x16x32_bf16 v[84:87], v[132:135], v[200:203], v[84:87]
	v_mfma_f32_16x16x32_bf16 v[80:83], v[140:143], v[200:203], v[80:83]
	v_mfma_f32_16x16x32_bf16 v[76:79], v[132:135], v[208:211], v[76:79]
	v_mfma_f32_16x16x32_bf16 v[72:75], v[140:143], v[208:211], v[72:75]
	v_mfma_f32_16x16x32_bf16 v[60:63], v[132:135], v[216:219], v[60:63]
	v_mfma_f32_16x16x32_bf16 v[56:59], v[140:143], v[216:219], v[56:59]
	s_setprio 0
	s_setprio 1
	v_mfma_f32_16x16x32_bf16 v[28:31], v[160:163], v[188:191], v[28:31]
	v_mfma_f32_16x16x32_bf16 v[24:27], v[180:183], v[188:191], v[24:27]
	v_mfma_f32_16x16x32_bf16 v[20:23], v[160:163], v[196:199], v[20:23]
	v_mfma_f32_16x16x32_bf16 v[16:19], v[180:183], v[196:199], v[16:19]
	v_mfma_f32_16x16x32_bf16 v[12:15], v[160:163], v[204:207], v[12:15]
	v_mfma_f32_16x16x32_bf16 v[8:11], v[180:183], v[204:207], v[8:11]
	v_mfma_f32_16x16x32_bf16 v[4:7], v[160:163], v[212:215], v[4:7]
	v_mfma_f32_16x16x32_bf16 v[0:3], v[180:183], v[212:215], v[0:3]
	v_mfma_f32_16x16x32_bf16 v[28:31], v[176:179], v[192:195], v[28:31]
	v_mfma_f32_16x16x32_bf16 v[24:27], v[184:187], v[192:195], v[24:27]
	v_mfma_f32_16x16x32_bf16 v[20:23], v[176:179], v[200:203], v[20:23]
	v_mfma_f32_16x16x32_bf16 v[16:19], v[184:187], v[200:203], v[16:19]
	v_mfma_f32_16x16x32_bf16 v[12:15], v[176:179], v[208:211], v[12:15]
	v_mfma_f32_16x16x32_bf16 v[8:11], v[184:187], v[208:211], v[8:11]
	v_mfma_f32_16x16x32_bf16 v[4:7], v[176:179], v[216:219], v[4:7]
	v_mfma_f32_16x16x32_bf16 v[0:3], v[184:187], v[216:219], v[0:3]
	s_setprio 0
	s_barrier
	s_add_i32 s74, s74, 2
	s_add_u32 s50, s50, 0x100
	s_addc_u32 s51, s51, 0
	s_add_u32 s84, s84, 0x100
	s_addc_u32 s85, s85, 0
	s_cmp_gt_u32 s74, 13
	s_cbranch_scc0 .LBB0_482
	s_and_b64 vcc, exec, s[10:11]
	s_cbranch_vccz .LBB0_485
	s_barrier

; #define PG8_STAGE(bufoff, gbase, voff) do { _Pragma("unroll") for (int _i = 0; _i < 2; ++_i) \
;         __builtin_amdgcn_global_load_lds((const unsigned*)((const char*)(gbase) + (voff)[_i]), (PG8_LAS unsigned*)(lds + (bufoff) + ldsw + _i * 8192), 16, 0, 0); } while (0)
; #define PG8_LDA(dst, b, h) do { _Pragma("unroll") for (int m = 0; m < 4; ++m) _Pragma("unroll") for (int k = 0; k < 2; ++k) dst[m][k] = *(const PG8_LAS bf16x8*)(lds + PG8_SA(b, h) + aoff + m * 2048 + k * 1024); } while (0)
; #define PG8_LDB(dst, b, h) do { _Pragma("unroll") for (int n = 0; n < 2; ++n) _Pragma("unroll") for (int k = 0; k < 2; ++k) dst[n][k] = *(const PG8_LAS bf16x8*)(lds + PG8_SB(b, h) + boff + n * 2048 + k * 1024); } while (0)
; #define PG8_MMA(ai, bj, At, Bt) do { __builtin_amdgcn_s_setprio(1); _Pragma("unroll") for (int m = 0; m < 4; ++m) _Pragma("unroll") for (int n = 0; n < 2; ++n) _Pragma("unroll") for (int k = 0; k < 2; ++k) \
;         acc[ai][bj][m][n] = __builtin_amdgcn_mfma_f32_16x16x32_bf16(Bt[n][k], At[m][k], acc[ai][bj][m][n], 0, 0, 0); __builtin_amdgcn_s_setprio(0); } while (0)
; #define PG8_WAIT_V(n) asm volatile("s_waitcnt vmcnt(" #n ")" ::: "memory")
; template <class Epi, class Sched, bool ALIGN_EPI = false, bool SP2 = false>
; __device__ __forceinline__ void gemm_phase(PG8_LAS unsigned char* lds, const Gemm g, const Sched& S, const Epi& E) {
;     ...
;             PG8_LDB(B0, 0, 0); PG8_LDB(B1, 0, 1); PG8_SCHED; PG8_LDA(At, 0, 0); PG8_STAGE(PG8_SA(1, 1), a1 + hstepA, voffA);
;             PG8_WAIT_V(8); PG8_WAIT_L(0); PG8_BAR; PG8_MMA(0, 0, At, B0); PG8_MMA(0, 1, At, B1); PG8_BAR; PG8_SCHED;
;             PG8_LDA(At, 0, 1); PG8_STAGE(PG8_SB(0, 0), b2, voffB); PG8_STAGE(PG8_SB(0, 1), b2 + hstepB, voffB); PG8_STAGE(PG8_SA(0, 0), a2, voffA);
;             PG8_WAIT_V(8); PG8_WAIT_L(0); PG8_BAR; PG8_MMA(1, 0, At, B0); PG8_MMA(1, 1, At, B1); PG8_BAR; PG8_SCHED;
;             PG8_LDB(B0, 1, 0); PG8_LDB(B1, 1, 1); PG8_SCHED; PG8_LDA(At, 1, 0); PG8_STAGE(PG8_SA(0, 1), a2 + hstepA, voffA);
;             PG8_WAIT_V(8); PG8_WAIT_L(0); PG8_BAR; PG8_MMA(0, 0, At, B0); PG8_MMA(0, 1, At, B1); PG8_BAR; PG8_SCHED;
;             PG8_LDA(At, 1, 1); PG8_STAGE(PG8_SB(1, 0), b3, voffB); PG8_STAGE(PG8_SB(1, 1), b3 + hstepB, voffB); PG8_STAGE(PG8_SA(1, 0), a3, voffA);
;             PG8_WAIT_V(8); PG8_WAIT_L(0); PG8_BAR; PG8_MMA(1, 0, At, B0); PG8_MMA(1, 1, At, B1); PG8_BAR; PG8_SCHED;
.LBB0_605:
	s_add_u32 s33, s38, 0xfffc0080
	s_addc_u32 s40, s39, -1
	s_cmp_eq_u32 s56, 12
	s_cselect_b32 s43, s13, s40
	s_cselect_b32 s42, s52, s33
	s_cselect_b32 s41, s11, s55
	s_cselect_b32 s40, s53, s54
	v_lshl_add_u64 v[216:217], s[38:39], 0, v[136:137]
	s_add_i32 m0, s29, 0xc000
	s_nop 0
	global_load_lds_dwordx4 v[216:217], off
	v_lshl_add_u64 v[216:217], s[38:39], 0, v[138:139]
	s_add_i32 m0, s29, 0xe000
	s_nop 0
	global_load_lds_dwordx4 v[216:217], off
	ds_read_b128 v[144:147], v151
	ds_read_b128 v[154:157], v151 offset:1024
	ds_read_b128 v[158:161], v151 offset:2048
	ds_read_b128 v[162:165], v151 offset:3072
	ds_read_b128 v[166:169], v152
	ds_read_b128 v[170:173], v152 offset:1024
	ds_read_b128 v[176:179], v152 offset:2048
	ds_read_b128 v[180:183], v152 offset:3072
	ds_read_b128 v[184:187], v153
	ds_read_b128 v[188:191], v153 offset:1024
	ds_read_b128 v[192:195], v153 offset:2048
	ds_read_b128 v[196:199], v153 offset:3072
	ds_read_b128 v[200:203], v153 offset:4096
	ds_read_b128 v[204:207], v153 offset:5120
	ds_read_b128 v[208:211], v153 offset:6144
	ds_read_b128 v[212:215], v153 offset:7168
	s_waitcnt vmcnt(8)
	s_waitcnt lgkmcnt(0)
	s_barrier
	s_setprio 1
	s_waitcnt lgkmcnt(0)
	v_mfma_f32_16x16x32_bf16 v[124:127], v[144:147], v[184:187], v[124:127]
	v_mfma_f32_16x16x32_bf16 v[120:123], v[158:161], v[184:187], v[120:123]
	v_mfma_f32_16x16x32_bf16 v[108:111], v[144:147], v[192:195], v[108:111]
	v_mfma_f32_16x16x32_bf16 v[104:107], v[158:161], v[192:195], v[104:107]
	v_mfma_f32_16x16x32_bf16 v[92:95], v[144:147], v[200:203], v[92:95]
	v_mfma_f32_16x16x32_bf16 v[88:91], v[158:161], v[200:203], v[88:91]
	v_mfma_f32_16x16x32_bf16 v[76:79], v[144:147], v[208:211], v[76:79]
	v_mfma_f32_16x16x32_bf16 v[72:75], v[158:161], v[208:211], v[72:75]
	v_mfma_f32_16x16x32_bf16 v[124:127], v[154:157], v[188:191], v[124:127]
	v_mfma_f32_16x16x32_bf16 v[120:123], v[162:165], v[188:191], v[120:123]
	v_mfma_f32_16x16x32_bf16 v[108:111], v[154:157], v[196:199], v[108:111]
	v_mfma_f32_16x16x32_bf16 v[104:107], v[162:165], v[196:199], v[104:107]
	v_mfma_f32_16x16x32_bf16 v[92:95], v[154:157], v[204:207], v[92:95]
	v_mfma_f32_16x16x32_bf16 v[88:91], v[162:165], v[204:207], v[88:91]
	v_mfma_f32_16x16x32_bf16 v[76:79], v[154:157], v[212:215], v[76:79]
	v_mfma_f32_16x16x32_bf16 v[72:75], v[162:165], v[212:215], v[72:75]
	s_setprio 0
	s_setprio 1
	v_mfma_f32_16x16x32_bf16 v[116:119], v[166:169], v[184:187], v[116:119]
	v_mfma_f32_16x16x32_bf16 v[112:115], v[176:179], v[184:187], v[112:115]
	v_mfma_f32_16x16x32_bf16 v[100:103], v[166:169], v[192:195], v[100:103]
	v_mfma_f32_16x16x32_bf16 v[96:99], v[176:179], v[192:195], v[96:99]
	v_mfma_f32_16x16x32_bf16 v[84:87], v[166:169], v[200:203], v[84:87]
	v_mfma_f32_16x16x32_bf16 v[80:83], v[176:179], v[200:203], v[80:83]
	v_mfma_f32_16x16x32_bf16 v[68:71], v[166:169], v[208:211], v[68:71]
	v_mfma_f32_16x16x32_bf16 v[64:67], v[176:179], v[208:211], v[64:67]
	v_mfma_f32_16x16x32_bf16 v[116:119], v[170:173], v[188:191], v[116:119]
	v_mfma_f32_16x16x32_bf16 v[112:115], v[180:183], v[188:191], v[112:115]
	v_mfma_f32_16x16x32_bf16 v[100:103], v[170:173], v[196:199], v[100:103]
	v_mfma_f32_16x16x32_bf16 v[96:99], v[180:183], v[196:199], v[96:99]
	v_mfma_f32_16x16x32_bf16 v[84:87], v[170:173], v[204:207], v[84:87]
	v_mfma_f32_16x16x32_bf16 v[80:83], v[180:183], v[204:207], v[80:83]
	v_mfma_f32_16x16x32_bf16 v[68:71], v[170:173], v[212:215], v[68:71]
	v_mfma_f32_16x16x32_bf16 v[64:67], v[180:183], v[212:215], v[64:67]
	s_setprio 0
	s_barrier
	s_add_i32 s33, s48, s22
	v_lshl_add_u64 v[216:217], s[40:41], 0, v[132:133]
	s_mov_b32 m0, s33
	s_nop 0
	global_load_lds_dwordx4 v[216:217], off
	s_add_i32 m0, s33, 0x2000
	s_add_u32 s58, s40, 0x40000
	v_lshl_add_u64 v[218:219], s[40:41], 0, v[128:129]
	s_addc_u32 s59, s41, 0
	s_add_i32 s33, s49, s22
	global_load_lds_dwordx4 v[218:219], off
	v_lshl_add_u64 v[220:221], s[58:59], 0, v[132:133]
	s_mov_b32 m0, s33
	v_lshl_add_u64 v[222:223], s[42:43], 0, v[130:131]
	global_load_lds_dwordx4 v[220:221], off
	v_lshl_add_u64 v[220:221], s[58:59], 0, v[128:129]
	s_add_i32 m0, s33, 0x2000
	s_nop 0
	global_load_lds_dwordx4 v[220:221], off
	v_lshl_add_u64 v[220:221], s[42:43], 0, v[134:135]
	s_mov_b32 m0, s29
	s_nop 0
	global_load_lds_dwordx4 v[220:221], off
	s_mov_b32 m0, s30
	s_nop 0
	global_load_lds_dwordx4 v[222:223], off
	ds_read_b128 v[184:187], v153 offset:16384
	ds_read_b128 v[188:191], v153 offset:17408
	ds_read_b128 v[192:195], v153 offset:18432
	ds_read_b128 v[196:199], v153 offset:19456
	ds_read_b128 v[200:203], v153 offset:20480
	ds_read_b128 v[204:207], v153 offset:21504
	ds_read_b128 v[208:211], v153 offset:22528
	ds_read_b128 v[212:215], v153 offset:23552
	s_waitcnt vmcnt(8)
	s_waitcnt lgkmcnt(0)
	s_barrier
; #define PG8_STAGE(bufoff, gbase, voff) do { _Pragma("unroll") for (int _i = 0; _i < 2; ++_i) \
;         __builtin_amdgcn_global_load_lds((const unsigned*)((const char*)(gbase) + (voff)[_i]), (PG8_LAS unsigned*)(lds + (bufoff) + ldsw + _i * 8192), 16, 0, 0); } while (0)
; #define PG8_LDA(dst, b, h) do { _Pragma("unroll") for (int m = 0; m < 4; ++m) _Pragma("unroll") for (int k = 0; k < 2; ++k) dst[m][k] = *(const PG8_LAS bf16x8*)(lds + PG8_SA(b, h) + aoff + m * 2048 + k * 1024); } while (0)
; #define PG8_LDB(dst, b, h) do { _Pragma("unroll") for (int n = 0; n < 2; ++n) _Pragma("unroll") for (int k = 0; k < 2; ++k) dst[n][k] = *(const PG8_LAS bf16x8*)(lds + PG8_SB(b, h) + boff + n * 2048 + k * 1024); } while (0)
; #define PG8_MMA(ai, bj, At, Bt) do { __builtin_amdgcn_s_setprio(1); _Pragma("unroll") for (int m = 0; m < 4; ++m) _Pragma("unroll") for (int n = 0; n < 2; ++n) _Pragma("unroll") for (int k = 0; k < 2; ++k) \
;         acc[ai][bj][m][n] = __builtin_amdgcn_mfma_f32_16x16x32_bf16(Bt[n][k], At[m][k], acc[ai][bj][m][n], 0, 0, 0); __builtin_amdgcn_s_setprio(0); } while (0)
; #define PG8_WAIT_V(n) asm volatile("s_waitcnt vmcnt(" #n ")" ::: "memory")
; template <class Epi, class Sched, bool ALIGN_EPI = false, bool SP2 = false>
; __device__ __forceinline__ void gemm_phase(PG8_LAS unsigned char* lds, const Gemm g, const Sched& S, const Epi& E) {
;     ...
;             PG8_LDB(B0, 0, 0); PG8_LDB(B1, 0, 1); PG8_SCHED; PG8_LDA(At, 0, 0); PG8_STAGE(PG8_SA(1, 1), a1 + hstepA, voffA);
;             PG8_WAIT_V(8); PG8_WAIT_L(0); PG8_BAR; PG8_MMA(0, 0, At, B0); PG8_MMA(0, 1, At, B1); PG8_BAR; PG8_SCHED;
;             PG8_LDA(At, 0, 1); PG8_STAGE(PG8_SB(0, 0), b2, voffB); PG8_STAGE(PG8_SB(0, 1), b2 + hstepB, voffB); PG8_STAGE(PG8_SA(0, 0), a2, voffA);
;             PG8_WAIT_V(8); PG8_WAIT_L(0); PG8_BAR; PG8_MMA(1, 0, At, B0); PG8_MMA(1, 1, At, B1); PG8_BAR; PG8_SCHED;
;             PG8_LDB(B0, 1, 0); PG8_LDB(B1, 1, 1); PG8_SCHED; PG8_LDA(At, 1, 0); PG8_STAGE(PG8_SA(0, 1), a2 + hstepA, voffA);
;             PG8_WAIT_V(8); PG8_WAIT_L(0); PG8_BAR; PG8_MMA(0, 0, At, B0); PG8_MMA(0, 1, At, B1); PG8_BAR; PG8_SCHED;
;             PG8_LDA(At, 1, 1); PG8_STAGE(PG8_SB(1, 0), b3, voffB); PG8_STAGE(PG8_SB(1, 1), b3 + hstepB, voffB); PG8_STAGE(PG8_SA(1, 0), a3, voffA);
;             PG8_WAIT_V(8); PG8_WAIT_L(0); PG8_BAR; PG8_MMA(1, 0, At, B0); PG8_MMA(1, 1, At, B1); PG8_BAR; PG8_SCHED;
	s_setprio 1
	s_waitcnt lgkmcnt(0)
	v_mfma_f32_16x16x32_bf16 v[60:63], v[144:147], v[184:187], v[60:63]
	v_mfma_f32_16x16x32_bf16 v[56:59], v[158:161], v[184:187], v[56:59]
	v_mfma_f32_16x16x32_bf16 v[44:47], v[144:147], v[192:195], v[44:47]
	v_mfma_f32_16x16x32_bf16 v[40:43], v[158:161], v[192:195], v[40:43]
	v_mfma_f32_16x16x32_bf16 v[28:31], v[144:147], v[200:203], v[28:31]
	v_mfma_f32_16x16x32_bf16 v[24:27], v[158:161], v[200:203], v[24:27]
	v_mfma_f32_16x16x32_bf16 v[12:15], v[144:147], v[208:211], v[12:15]
	v_mfma_f32_16x16x32_bf16 v[8:11], v[158:161], v[208:211], v[8:11]
	v_mfma_f32_16x16x32_bf16 v[60:63], v[154:157], v[188:191], v[60:63]
	v_mfma_f32_16x16x32_bf16 v[56:59], v[162:165], v[188:191], v[56:59]
	v_mfma_f32_16x16x32_bf16 v[44:47], v[154:157], v[196:199], v[44:47]
	v_mfma_f32_16x16x32_bf16 v[40:43], v[162:165], v[196:199], v[40:43]
	v_mfma_f32_16x16x32_bf16 v[28:31], v[154:157], v[204:207], v[28:31]
	v_mfma_f32_16x16x32_bf16 v[24:27], v[162:165], v[204:207], v[24:27]
	v_mfma_f32_16x16x32_bf16 v[12:15], v[154:157], v[212:215], v[12:15]
	v_mfma_f32_16x16x32_bf16 v[8:11], v[162:165], v[212:215], v[8:11]
	s_setprio 0
	s_setprio 1
	v_mfma_f32_16x16x32_bf16 v[52:55], v[166:169], v[184:187], v[52:55]
	v_mfma_f32_16x16x32_bf16 v[48:51], v[176:179], v[184:187], v[48:51]
	v_mfma_f32_16x16x32_bf16 v[36:39], v[166:169], v[192:195], v[36:39]
	v_mfma_f32_16x16x32_bf16 v[32:35], v[176:179], v[192:195], v[32:35]
	v_mfma_f32_16x16x32_bf16 v[20:23], v[166:169], v[200:203], v[20:23]
	v_mfma_f32_16x16x32_bf16 v[16:19], v[176:179], v[200:203], v[16:19]
	v_mfma_f32_16x16x32_bf16 v[4:7], v[166:169], v[208:211], v[4:7]
	v_mfma_f32_16x16x32_bf16 v[0:3], v[176:179], v[208:211], v[0:3]
	v_mfma_f32_16x16x32_bf16 v[52:55], v[170:173], v[188:191], v[52:55]
	v_mfma_f32_16x16x32_bf16 v[48:51], v[180:183], v[188:191], v[48:51]
	v_mfma_f32_16x16x32_bf16 v[36:39], v[170:173], v[196:199], v[36:39]
	v_mfma_f32_16x16x32_bf16 v[32:35], v[180:183], v[196:199], v[32:35]
	v_mfma_f32_16x16x32_bf16 v[20:23], v[170:173], v[204:207], v[20:23]
	v_mfma_f32_16x16x32_bf16 v[16:19], v[180:183], v[204:207], v[16:19]
	v_mfma_f32_16x16x32_bf16 v[4:7], v[170:173], v[212:215], v[4:7]
	v_mfma_f32_16x16x32_bf16 v[0:3], v[180:183], v[212:215], v[0:3]
	s_setprio 0
	s_barrier
	s_add_i32 s33, 0, 0x18000
	s_add_i32 s57, 0, 0x1c000
	v_add_u32_e32 v162, s33, v149
	v_add_u32_e32 v175, s57, v149
	s_add_u32 s42, s42, 0x40000
	s_addc_u32 s43, s43, 0
	s_mov_b32 m0, s31
	v_lshl_add_u64 v[224:225], s[42:43], 0, v[134:135]
	global_load_lds_dwordx4 v[224:225], off
	v_lshl_add_u64 v[224:225], s[42:43], 0, v[130:131]
	s_mov_b32 m0, s35
	s_nop 0
	global_load_lds_dwordx4 v[224:225], off
	ds_read_b128 v[144:147], v162
	ds_read_b128 v[154:157], v162 offset:1024
	ds_read_b128 v[158:161], v162 offset:2048
	ds_read_b128 v[162:165], v162 offset:3072
	ds_read_b128 v[166:169], v175
	ds_read_b128 v[170:173], v175 offset:1024
	ds_read_b128 v[176:179], v175 offset:2048
	ds_read_b128 v[180:183], v175 offset:3072
	ds_read_b128 v[184:187], v153 offset:32768
	ds_read_b128 v[188:191], v153 offset:33792
	ds_read_b128 v[192:195], v153 offset:34816
	ds_read_b128 v[196:199], v153 offset:35840
	ds_read_b128 v[200:203], v153 offset:36864
	ds_read_b128 v[204:207], v153 offset:37888
	ds_read_b128 v[208:211], v153 offset:38912
	ds_read_b128 v[212:215], v153 offset:39936
	s_waitcnt vmcnt(8)
	s_waitcnt lgkmcnt(0)
	s_barrier
	s_setprio 1
	s_waitcnt lgkmcnt(0)
	v_mfma_f32_16x16x32_bf16 v[124:127], v[144:147], v[184:187], v[124:127]
	v_mfma_f32_16x16x32_bf16 v[120:123], v[158:161], v[184:187], v[120:123]
	v_mfma_f32_16x16x32_bf16 v[108:111], v[144:147], v[192:195], v[108:111]
	v_mfma_f32_16x16x32_bf16 v[104:107], v[158:161], v[192:195], v[104:107]
	v_mfma_f32_16x16x32_bf16 v[92:95], v[144:147], v[200:203], v[92:95]
	v_mfma_f32_16x16x32_bf16 v[88:91], v[158:161], v[200:203], v[88:91]
	v_mfma_f32_16x16x32_bf16 v[76:79], v[144:147], v[208:211], v[76:79]
	v_mfma_f32_16x16x32_bf16 v[72:75], v[158:161], v[208:211], v[72:75]
	v_mfma_f32_16x16x32_bf16 v[124:127], v[154:157], v[188:191], v[124:127]
	v_mfma_f32_16x16x32_bf16 v[120:123], v[162:165], v[188:191], v[120:123]
	v_mfma_f32_16x16x32_bf16 v[108:111], v[154:157], v[196:199], v[108:111]
	v_mfma_f32_16x16x32_bf16 v[104:107], v[162:165], v[196:199], v[104:107]
	v_mfma_f32_16x16x32_bf16 v[92:95], v[154:157], v[204:207], v[92:95]
	v_mfma_f32_16x16x32_bf16 v[88:91], v[162:165], v[204:207], v[88:91]
	v_mfma_f32_16x16x32_bf16 v[76:79], v[154:157], v[212:215], v[76:79]
	v_mfma_f32_16x16x32_bf16 v[72:75], v[162:165], v[212:215], v[72:75]
	s_setprio 0
	s_setprio 1
	v_mfma_f32_16x16x32_bf16 v[116:119], v[166:169], v[184:187], v[116:119]
	v_mfma_f32_16x16x32_bf16 v[112:115], v[176:179], v[184:187], v[112:115]
	v_mfma_f32_16x16x32_bf16 v[100:103], v[166:169], v[192:195], v[100:103]
	v_mfma_f32_16x16x32_bf16 v[96:99], v[176:179], v[192:195], v[96:99]
	v_mfma_f32_16x16x32_bf16 v[84:87], v[166:169], v[200:203], v[84:87]
	v_mfma_f32_16x16x32_bf16 v[80:83], v[176:179], v[200:203], v[80:83]
	v_mfma_f32_16x16x32_bf16 v[68:71], v[166:169], v[208:211], v[68:71]
	v_mfma_f32_16x16x32_bf16 v[64:67], v[176:179], v[208:211], v[64:67]
	v_mfma_f32_16x16x32_bf16 v[116:119], v[170:173], v[188:191], v[116:119]
	v_mfma_f32_16x16x32_bf16 v[112:115], v[180:183], v[188:191], v[112:115]
	v_mfma_f32_16x16x32_bf16 v[100:103], v[170:173], v[196:199], v[100:103]
	v_mfma_f32_16x16x32_bf16 v[96:99], v[180:183], v[196:199], v[96:99]
	v_mfma_f32_16x16x32_bf16 v[84:87], v[170:173], v[204:207], v[84:87]
	v_mfma_f32_16x16x32_bf16 v[80:83], v[180:183], v[204:207], v[80:83]
	v_mfma_f32_16x16x32_bf16 v[68:71], v[170:173], v[212:215], v[68:71]
	v_mfma_f32_16x16x32_bf16 v[64:67], v[180:183], v[212:215], v[64:67]
	s_setprio 0
	s_barrier
; #define PG8_STAGE(bufoff, gbase, voff) do { _Pragma("unroll") for (int _i = 0; _i < 2; ++_i) \
;         __builtin_amdgcn_global_load_lds((const unsigned*)((const char*)(gbase) + (voff)[_i]), (PG8_LAS unsigned*)(lds + (bufoff) + ldsw + _i * 8192), 16, 0, 0); } while (0)
; #define PG8_LDA(dst, b, h) do { _Pragma("unroll") for (int m = 0; m < 4; ++m) _Pragma("unroll") for (int k = 0; k < 2; ++k) dst[m][k] = *(const PG8_LAS bf16x8*)(lds + PG8_SA(b, h) + aoff + m * 2048 + k * 1024); } while (0)
; #define PG8_LDB(dst, b, h) do { _Pragma("unroll") for (int n = 0; n < 2; ++n) _Pragma("unroll") for (int k = 0; k < 2; ++k) dst[n][k] = *(const PG8_LAS bf16x8*)(lds + PG8_SB(b, h) + boff + n * 2048 + k * 1024); } while (0)
; #define PG8_MMA(ai, bj, At, Bt) do { __builtin_amdgcn_s_setprio(1); _Pragma("unroll") for (int m = 0; m < 4; ++m) _Pragma("unroll") for (int n = 0; n < 2; ++n) _Pragma("unroll") for (int k = 0; k < 2; ++k) \
;         acc[ai][bj][m][n] = __builtin_amdgcn_mfma_f32_16x16x32_bf16(Bt[n][k], At[m][k], acc[ai][bj][m][n], 0, 0, 0); __builtin_amdgcn_s_setprio(0); } while (0)
; #define PG8_WAIT_V(n) asm volatile("s_waitcnt vmcnt(" #n ")" ::: "memory")
; template <class Epi, class Sched, bool ALIGN_EPI = false, bool SP2 = false>
; __device__ __forceinline__ void gemm_phase(PG8_LAS unsigned char* lds, const Gemm g, const Sched& S, const Epi& E) {
;     ...
;             PG8_LDB(B0, 0, 0); PG8_LDB(B1, 0, 1); PG8_SCHED; PG8_LDA(At, 0, 0); PG8_STAGE(PG8_SA(1, 1), a1 + hstepA, voffA);
;             PG8_WAIT_V(8); PG8_WAIT_L(0); PG8_BAR; PG8_MMA(0, 0, At, B0); PG8_MMA(0, 1, At, B1); PG8_BAR; PG8_SCHED;
;             PG8_LDA(At, 0, 1); PG8_STAGE(PG8_SB(0, 0), b2, voffB); PG8_STAGE(PG8_SB(0, 1), b2 + hstepB, voffB); PG8_STAGE(PG8_SA(0, 0), a2, voffA);
;             PG8_WAIT_V(8); PG8_WAIT_L(0); PG8_BAR; PG8_MMA(1, 0, At, B0); PG8_MMA(1, 1, At, B1); PG8_BAR; PG8_SCHED;
;             PG8_LDB(B0, 1, 0); PG8_LDB(B1, 1, 1); PG8_SCHED; PG8_LDA(At, 1, 0); PG8_STAGE(PG8_SA(0, 1), a2 + hstepA, voffA);
;             PG8_WAIT_V(8); PG8_WAIT_L(0); PG8_BAR; PG8_MMA(0, 0, At, B0); PG8_MMA(0, 1, At, B1); PG8_BAR; PG8_SCHED;
;             PG8_LDA(At, 1, 1); PG8_STAGE(PG8_SB(1, 0), b3, voffB); PG8_STAGE(PG8_SB(1, 1), b3 + hstepB, voffB); PG8_STAGE(PG8_SA(1, 0), a3, voffA);
;             PG8_WAIT_V(8); PG8_WAIT_L(0); PG8_BAR; PG8_MMA(1, 0, At, B0); PG8_MMA(1, 1, At, B1); PG8_BAR; PG8_SCHED;
	s_add_i32 s33, s33, s22
	v_lshl_add_u64 v[216:217], v[216:217], 0, s[6:7]
	s_mov_b32 m0, s33
	s_nop 0
	global_load_lds_dwordx4 v[216:217], off
	s_add_i32 m0, s33, 0x2000
	s_add_u32 s40, s40, 0x40080
	v_lshl_add_u64 v[216:217], v[218:219], 0, s[6:7]
	s_addc_u32 s41, s41, 0
	s_add_i32 s33, s57, s22
	global_load_lds_dwordx4 v[216:217], off
	v_lshl_add_u64 v[216:217], s[40:41], 0, v[132:133]
	s_mov_b32 m0, s33
	s_nop 0
	global_load_lds_dwordx4 v[216:217], off
	v_lshl_add_u64 v[216:217], s[40:41], 0, v[128:129]
	s_add_i32 m0, s33, 0x2000
	s_nop 0
	global_load_lds_dwordx4 v[216:217], off
	v_lshl_add_u64 v[216:217], v[220:221], 0, s[6:7]
	s_mov_b32 m0, s44
	s_nop 0
	global_load_lds_dwordx4 v[216:217], off
	v_lshl_add_u64 v[216:217], v[222:223], 0, s[6:7]
	s_mov_b32 m0, s45
	s_nop 0
	global_load_lds_dwordx4 v[216:217], off
	ds_read_b128 v[184:187], v153 offset:49152
	ds_read_b128 v[188:191], v153 offset:50176
	ds_read_b128 v[192:195], v153 offset:51200
	ds_read_b128 v[196:199], v153 offset:52224
	ds_read_b128 v[200:203], v153 offset:53248
	ds_read_b128 v[204:207], v153 offset:54272
	ds_read_b128 v[208:211], v153 offset:55296
	ds_read_b128 v[212:215], v153 offset:56320
	s_waitcnt vmcnt(8)
	s_waitcnt lgkmcnt(0)
	s_barrier
	s_setprio 1
	s_waitcnt lgkmcnt(0)
	v_mfma_f32_16x16x32_bf16 v[60:63], v[144:147], v[184:187], v[60:63]
	v_mfma_f32_16x16x32_bf16 v[56:59], v[158:161], v[184:187], v[56:59]
	v_mfma_f32_16x16x32_bf16 v[44:47], v[144:147], v[192:195], v[44:47]
	v_mfma_f32_16x16x32_bf16 v[40:43], v[158:161], v[192:195], v[40:43]
	v_mfma_f32_16x16x32_bf16 v[28:31], v[144:147], v[200:203], v[28:31]
	v_mfma_f32_16x16x32_bf16 v[24:27], v[158:161], v[200:203], v[24:27]
	v_mfma_f32_16x16x32_bf16 v[12:15], v[144:147], v[208:211], v[12:15]
	v_mfma_f32_16x16x32_bf16 v[8:11], v[158:161], v[208:211], v[8:11]
	v_mfma_f32_16x16x32_bf16 v[60:63], v[154:157], v[188:191], v[60:63]
	v_mfma_f32_16x16x32_bf16 v[56:59], v[162:165], v[188:191], v[56:59]
	v_mfma_f32_16x16x32_bf16 v[44:47], v[154:157], v[196:199], v[44:47]
	v_mfma_f32_16x16x32_bf16 v[40:43], v[162:165], v[196:199], v[40:43]
	v_mfma_f32_16x16x32_bf16 v[28:31], v[154:157], v[204:207], v[28:31]
	v_mfma_f32_16x16x32_bf16 v[24:27], v[162:165], v[204:207], v[24:27]
	v_mfma_f32_16x16x32_bf16 v[12:15], v[154:157], v[212:215], v[12:15]
	v_mfma_f32_16x16x32_bf16 v[8:11], v[162:165], v[212:215], v[8:11]
	s_setprio 0
	s_setprio 1
	v_mfma_f32_16x16x32_bf16 v[52:55], v[166:169], v[184:187], v[52:55]
	v_mfma_f32_16x16x32_bf16 v[48:51], v[176:179], v[184:187], v[48:51]
	v_mfma_f32_16x16x32_bf16 v[36:39], v[166:169], v[192:195], v[36:39]
	v_mfma_f32_16x16x32_bf16 v[32:35], v[176:179], v[192:195], v[32:35]
	v_mfma_f32_16x16x32_bf16 v[20:23], v[166:169], v[200:203], v[20:23]
	v_mfma_f32_16x16x32_bf16 v[16:19], v[176:179], v[200:203], v[16:19]
	v_mfma_f32_16x16x32_bf16 v[4:7], v[166:169], v[208:211], v[4:7]
	v_mfma_f32_16x16x32_bf16 v[0:3], v[176:179], v[208:211], v[0:3]
	v_mfma_f32_16x16x32_bf16 v[52:55], v[170:173], v[188:191], v[52:55]
	v_mfma_f32_16x16x32_bf16 v[48:51], v[180:183], v[188:191], v[48:51]
	v_mfma_f32_16x16x32_bf16 v[36:39], v[170:173], v[196:199], v[36:39]
	v_mfma_f32_16x16x32_bf16 v[32:35], v[180:183], v[196:199], v[32:35]
	v_mfma_f32_16x16x32_bf16 v[20:23], v[170:173], v[204:207], v[20:23]
	v_mfma_f32_16x16x32_bf16 v[16:19], v[180:183], v[204:207], v[16:19]
	v_mfma_f32_16x16x32_bf16 v[4:7], v[170:173], v[212:215], v[4:7]
	v_mfma_f32_16x16x32_bf16 v[0:3], v[180:183], v[212:215], v[0:3]
	s_setprio 0
	s_barrier
	s_add_i32 s56, s56, 2
	s_add_u32 s38, s38, 0x100
	s_addc_u32 s39, s39, 0
	s_add_u32 s54, s54, 0x100
	s_addc_u32 s55, s55, 0
	s_cmp_gt_u32 s56, 13
	s_cbranch_scc0 .LBB0_605
	s_and_b64 vcc, exec, s[8:9]
	s_cbranch_vccz .LBB0_608
	s_barrier

; #define PG8_STAGE(bufoff, gbase, voff) do { _Pragma("unroll") for (int _i = 0; _i < 2; ++_i) \
;         __builtin_amdgcn_global_load_lds((const unsigned*)((const char*)(gbase) + (voff)[_i]), (PG8_LAS unsigned*)(lds + (bufoff) + ldsw + _i * 8192), 16, 0, 0); } while (0)
; #define PG8_LDA(dst, b, h) do { _Pragma("unroll") for (int m = 0; m < 4; ++m) _Pragma("unroll") for (int k = 0; k < 2; ++k) dst[m][k] = *(const PG8_LAS bf16x8*)(lds + PG8_SA(b, h) + aoff + m * 2048 + k * 1024); } while (0)
; #define PG8_LDB(dst, b, h) do { _Pragma("unroll") for (int n = 0; n < 2; ++n) _Pragma("unroll") for (int k = 0; k < 2; ++k) dst[n][k] = *(const PG8_LAS bf16x8*)(lds + PG8_SB(b, h) + boff + n * 2048 + k * 1024); } while (0)
; #define PG8_MMA(ai, bj, At, Bt) do { __builtin_amdgcn_s_setprio(1); _Pragma("unroll") for (int m = 0; m < 4; ++m) _Pragma("unroll") for (int n = 0; n < 2; ++n) _Pragma("unroll") for (int k = 0; k < 2; ++k) \
;         acc[ai][bj][m][n] = __builtin_amdgcn_mfma_f32_16x16x32_bf16(Bt[n][k], At[m][k], acc[ai][bj][m][n], 0, 0, 0); __builtin_amdgcn_s_setprio(0); } while (0)
; #define PG8_WAIT_V(n) asm volatile("s_waitcnt vmcnt(" #n ")" ::: "memory")
; template <class Epi, class Sched, bool ALIGN_EPI = false, bool SP2 = false>
; __device__ __forceinline__ void gemm_phase(PG8_LAS unsigned char* lds, const Gemm g, const Sched& S, const Epi& E) {
;     ...
;             PG8_LDB(B0, 0, 0); PG8_LDB(B1, 0, 1); PG8_SCHED; PG8_LDA(At, 0, 0); PG8_STAGE(PG8_SA(1, 1), a1 + hstepA, voffA);
;             PG8_WAIT_V(8); PG8_WAIT_L(0); PG8_BAR; PG8_MMA(0, 0, At, B0); PG8_MMA(0, 1, At, B1); PG8_BAR; PG8_SCHED;
;             PG8_LDA(At, 0, 1); PG8_STAGE(PG8_SB(0, 0), b2, voffB); PG8_STAGE(PG8_SB(0, 1), b2 + hstepB, voffB); PG8_STAGE(PG8_SA(0, 0), a2, voffA);
;             PG8_WAIT_V(8); PG8_WAIT_L(0); PG8_BAR; PG8_MMA(1, 0, At, B0); PG8_MMA(1, 1, At, B1); PG8_BAR; PG8_SCHED;
;             PG8_LDB(B0, 1, 0); PG8_LDB(B1, 1, 1); PG8_SCHED; PG8_LDA(At, 1, 0); PG8_STAGE(PG8_SA(0, 1), a2 + hstepA, voffA);
;             PG8_WAIT_V(8); PG8_WAIT_L(0); PG8_BAR; PG8_MMA(0, 0, At, B0); PG8_MMA(0, 1, At, B1); PG8_BAR; PG8_SCHED;
;             PG8_LDA(At, 1, 1); PG8_STAGE(PG8_SB(1, 0), b3, voffB); PG8_STAGE(PG8_SB(1, 1), b3 + hstepB, voffB); PG8_STAGE(PG8_SA(1, 0), a3, voffA);
;             PG8_WAIT_V(8); PG8_WAIT_L(0); PG8_BAR; PG8_MMA(1, 0, At, B0); PG8_MMA(1, 1, At, B1); PG8_BAR; PG8_SCHED;
.Lpeel_p7:
	ds_read_b128 v[144:147], v151
	ds_read_b128 v[154:157], v151 offset:1024
	ds_read_b128 v[158:161], v151 offset:2048
	ds_read_b128 v[162:165], v151 offset:3072
	ds_read_b128 v[166:169], v152
	ds_read_b128 v[170:173], v152 offset:1024
	ds_read_b128 v[176:179], v152 offset:2048
	ds_read_b128 v[180:183], v152 offset:3072
	s_add_u32 s33, s38, 0xfffc0080
	s_addc_u32 s40, s39, -1
	s_cmp_eq_u32 s56, 12
	s_cselect_b32 s43, s13, s40
	s_cselect_b32 s42, s52, s33
	s_cselect_b32 s41, s11, s55
	s_cselect_b32 s40, s53, s54
	ds_read_b128 v[184:187], v153
	ds_read_b128 v[188:191], v153 offset:1024
	ds_read_b128 v[192:195], v153 offset:2048
	ds_read_b128 v[196:199], v153 offset:3072
	ds_read_b128 v[200:203], v153 offset:4096
	ds_read_b128 v[204:207], v153 offset:5120
	ds_read_b128 v[208:211], v153 offset:6144
	ds_read_b128 v[212:215], v153 offset:7168
	s_waitcnt vmcnt(16)
	s_waitcnt lgkmcnt(0)
	s_barrier
	s_setprio 1
	s_waitcnt lgkmcnt(0)
	v_mfma_f32_16x16x32_bf16 v[124:127], v[144:147], v[184:187], 0
	v_mfma_f32_16x16x32_bf16 v[120:123], v[158:161], v[184:187], 0
	v_mfma_f32_16x16x32_bf16 v[108:111], v[144:147], v[192:195], 0
	v_mfma_f32_16x16x32_bf16 v[104:107], v[158:161], v[192:195], 0
	v_mfma_f32_16x16x32_bf16 v[92:95], v[144:147], v[200:203], 0
	v_mfma_f32_16x16x32_bf16 v[88:91], v[158:161], v[200:203], 0
	v_mfma_f32_16x16x32_bf16 v[76:79], v[144:147], v[208:211], 0
	v_mfma_f32_16x16x32_bf16 v[72:75], v[158:161], v[208:211], 0
	v_mfma_f32_16x16x32_bf16 v[124:127], v[154:157], v[188:191], v[124:127]
	v_mfma_f32_16x16x32_bf16 v[120:123], v[162:165], v[188:191], v[120:123]
	v_mfma_f32_16x16x32_bf16 v[108:111], v[154:157], v[196:199], v[108:111]
	v_mfma_f32_16x16x32_bf16 v[104:107], v[162:165], v[196:199], v[104:107]
	v_mfma_f32_16x16x32_bf16 v[92:95], v[154:157], v[204:207], v[92:95]
	v_mfma_f32_16x16x32_bf16 v[88:91], v[162:165], v[204:207], v[88:91]
	v_mfma_f32_16x16x32_bf16 v[76:79], v[154:157], v[212:215], v[76:79]
	v_mfma_f32_16x16x32_bf16 v[72:75], v[162:165], v[212:215], v[72:75]
	s_setprio 0
	s_setprio 1
	v_mfma_f32_16x16x32_bf16 v[116:119], v[166:169], v[184:187], 0
	v_mfma_f32_16x16x32_bf16 v[112:115], v[176:179], v[184:187], 0
	v_mfma_f32_16x16x32_bf16 v[100:103], v[166:169], v[192:195], 0
	v_mfma_f32_16x16x32_bf16 v[96:99], v[176:179], v[192:195], 0
	v_mfma_f32_16x16x32_bf16 v[84:87], v[166:169], v[200:203], 0
	v_mfma_f32_16x16x32_bf16 v[80:83], v[176:179], v[200:203], 0
	v_mfma_f32_16x16x32_bf16 v[68:71], v[166:169], v[208:211], 0
	v_mfma_f32_16x16x32_bf16 v[64:67], v[176:179], v[208:211], 0
	v_mfma_f32_16x16x32_bf16 v[116:119], v[170:173], v[188:191], v[116:119]
	v_mfma_f32_16x16x32_bf16 v[112:115], v[180:183], v[188:191], v[112:115]
	v_mfma_f32_16x16x32_bf16 v[100:103], v[170:173], v[196:199], v[100:103]
	v_mfma_f32_16x16x32_bf16 v[96:99], v[180:183], v[196:199], v[96:99]
	v_mfma_f32_16x16x32_bf16 v[84:87], v[170:173], v[204:207], v[84:87]
	v_mfma_f32_16x16x32_bf16 v[80:83], v[180:183], v[204:207], v[80:83]
	v_mfma_f32_16x16x32_bf16 v[68:71], v[170:173], v[212:215], v[68:71]
	v_mfma_f32_16x16x32_bf16 v[64:67], v[180:183], v[212:215], v[64:67]
	s_setprio 0
	s_barrier
	s_add_i32 s33, s48, s22
	v_lshl_add_u64 v[216:217], s[40:41], 0, v[132:133]
	s_mov_b32 m0, s33
	s_nop 0
	global_load_lds_dwordx4 v[216:217], off
	s_add_i32 m0, s33, 0x2000
	s_add_u32 s58, s40, 0x40000
	v_lshl_add_u64 v[218:219], s[40:41], 0, v[128:129]
	s_addc_u32 s59, s41, 0
	s_add_i32 s33, s49, s22
	global_load_lds_dwordx4 v[218:219], off
	v_lshl_add_u64 v[220:221], s[58:59], 0, v[132:133]
	s_mov_b32 m0, s33
	v_lshl_add_u64 v[222:223], s[42:43], 0, v[130:131]
	global_load_lds_dwordx4 v[220:221], off
	v_lshl_add_u64 v[220:221], s[58:59], 0, v[128:129]
	s_add_i32 m0, s33, 0x2000
	s_nop 0
	global_load_lds_dwordx4 v[220:221], off
	v_lshl_add_u64 v[220:221], s[42:43], 0, v[134:135]
	s_mov_b32 m0, s29
	s_nop 0
	global_load_lds_dwordx4 v[220:221], off
	s_mov_b32 m0, s30
	s_nop 0
	global_load_lds_dwordx4 v[222:223], off
	ds_read_b128 v[184:187], v153 offset:16384
	ds_read_b128 v[188:191], v153 offset:17408
	ds_read_b128 v[192:195], v153 offset:18432
	ds_read_b128 v[196:199], v153 offset:19456
	ds_read_b128 v[200:203], v153 offset:20480
	ds_read_b128 v[204:207], v153 offset:21504
	ds_read_b128 v[208:211], v153 offset:22528
	ds_read_b128 v[212:215], v153 offset:23552
	s_waitcnt vmcnt(16)
	s_waitcnt lgkmcnt(0)
	s_barrier
	s_setprio 1
	s_waitcnt lgkmcnt(0)
	v_mfma_f32_16x16x32_bf16 v[60:63], v[144:147], v[184:187], 0
	v_mfma_f32_16x16x32_bf16 v[56:59], v[158:161], v[184:187], 0
	v_mfma_f32_16x16x32_bf16 v[44:47], v[144:147], v[192:195], 0
	v_mfma_f32_16x16x32_bf16 v[40:43], v[158:161], v[192:195], 0
	v_mfma_f32_16x16x32_bf16 v[28:31], v[144:147], v[200:203], 0
	v_mfma_f32_16x16x32_bf16 v[24:27], v[158:161], v[200:203], 0
	v_mfma_f32_16x16x32_bf16 v[12:15], v[144:147], v[208:211], 0
	v_mfma_f32_16x16x32_bf16 v[8:11], v[158:161], v[208:211], 0
	v_mfma_f32_16x16x32_bf16 v[60:63], v[154:157], v[188:191], v[60:63]
	v_mfma_f32_16x16x32_bf16 v[56:59], v[162:165], v[188:191], v[56:59]
	v_mfma_f32_16x16x32_bf16 v[44:47], v[154:157], v[196:199], v[44:47]
	v_mfma_f32_16x16x32_bf16 v[40:43], v[162:165], v[196:199], v[40:43]
	v_mfma_f32_16x16x32_bf16 v[28:31], v[154:157], v[204:207], v[28:31]
	v_mfma_f32_16x16x32_bf16 v[24:27], v[162:165], v[204:207], v[24:27]
	v_mfma_f32_16x16x32_bf16 v[12:15], v[154:157], v[212:215], v[12:15]
	v_mfma_f32_16x16x32_bf16 v[8:11], v[162:165], v[212:215], v[8:11]
	s_setprio 0
	s_setprio 1
	v_mfma_f32_16x16x32_bf16 v[52:55], v[166:169], v[184:187], 0
	v_mfma_f32_16x16x32_bf16 v[48:51], v[176:179], v[184:187], 0
	v_mfma_f32_16x16x32_bf16 v[36:39], v[166:169], v[192:195], 0
	v_mfma_f32_16x16x32_bf16 v[32:35], v[176:179], v[192:195], 0
	v_mfma_f32_16x16x32_bf16 v[20:23], v[166:169], v[200:203], 0
	v_mfma_f32_16x16x32_bf16 v[16:19], v[176:179], v[200:203], 0
	v_mfma_f32_16x16x32_bf16 v[4:7], v[166:169], v[208:211], 0
	v_mfma_f32_16x16x32_bf16 v[0:3], v[176:179], v[208:211], 0
	v_mfma_f32_16x16x32_bf16 v[52:55], v[170:173], v[188:191], v[52:55]
	v_mfma_f32_16x16x32_bf16 v[48:51], v[180:183], v[188:191], v[48:51]
	v_mfma_f32_16x16x32_bf16 v[36:39], v[170:173], v[196:199], v[36:39]
	v_mfma_f32_16x16x32_bf16 v[32:35], v[180:183], v[196:199], v[32:35]
	v_mfma_f32_16x16x32_bf16 v[20:23], v[170:173], v[204:207], v[20:23]
	v_mfma_f32_16x16x32_bf16 v[16:19], v[180:183], v[204:207], v[16:19]
	v_mfma_f32_16x16x32_bf16 v[4:7], v[170:173], v[212:215], v[4:7]
	v_mfma_f32_16x16x32_bf16 v[0:3], v[180:183], v[212:215], v[0:3]
	s_setprio 0
	s_barrier
; #define PG8_STAGE(bufoff, gbase, voff) do { _Pragma("unroll") for (int _i = 0; _i < 2; ++_i) \
;         __builtin_amdgcn_global_load_lds((const unsigned*)((const char*)(gbase) + (voff)[_i]), (PG8_LAS unsigned*)(lds + (bufoff) + ldsw + _i * 8192), 16, 0, 0); } while (0)
; #define PG8_LDA(dst, b, h) do { _Pragma("unroll") for (int m = 0; m < 4; ++m) _Pragma("unroll") for (int k = 0; k < 2; ++k) dst[m][k] = *(const PG8_LAS bf16x8*)(lds + PG8_SA(b, h) + aoff + m * 2048 + k * 1024); } while (0)
; #define PG8_LDB(dst, b, h) do { _Pragma("unroll") for (int n = 0; n < 2; ++n) _Pragma("unroll") for (int k = 0; k < 2; ++k) dst[n][k] = *(const PG8_LAS bf16x8*)(lds + PG8_SB(b, h) + boff + n * 2048 + k * 1024); } while (0)
; #define PG8_MMA(ai, bj, At, Bt) do { __builtin_amdgcn_s_setprio(1); _Pragma("unroll") for (int m = 0; m < 4; ++m) _Pragma("unroll") for (int n = 0; n < 2; ++n) _Pragma("unroll") for (int k = 0; k < 2; ++k) \
;         acc[ai][bj][m][n] = __builtin_amdgcn_mfma_f32_16x16x32_bf16(Bt[n][k], At[m][k], acc[ai][bj][m][n], 0, 0, 0); __builtin_amdgcn_s_setprio(0); } while (0)
; #define PG8_WAIT_V(n) asm volatile("s_waitcnt vmcnt(" #n ")" ::: "memory")
; template <class Epi, class Sched, bool ALIGN_EPI = false, bool SP2 = false>
; __device__ __forceinline__ void gemm_phase(PG8_LAS unsigned char* lds, const Gemm g, const Sched& S, const Epi& E) {
;     ...
;             PG8_LDB(B0, 0, 0); PG8_LDB(B1, 0, 1); PG8_SCHED; PG8_LDA(At, 0, 0); PG8_STAGE(PG8_SA(1, 1), a1 + hstepA, voffA);
;             PG8_WAIT_V(8); PG8_WAIT_L(0); PG8_BAR; PG8_MMA(0, 0, At, B0); PG8_MMA(0, 1, At, B1); PG8_BAR; PG8_SCHED;
;             PG8_LDA(At, 0, 1); PG8_STAGE(PG8_SB(0, 0), b2, voffB); PG8_STAGE(PG8_SB(0, 1), b2 + hstepB, voffB); PG8_STAGE(PG8_SA(0, 0), a2, voffA);
;             PG8_WAIT_V(8); PG8_WAIT_L(0); PG8_BAR; PG8_MMA(1, 0, At, B0); PG8_MMA(1, 1, At, B1); PG8_BAR; PG8_SCHED;
;             PG8_LDB(B0, 1, 0); PG8_LDB(B1, 1, 1); PG8_SCHED; PG8_LDA(At, 1, 0); PG8_STAGE(PG8_SA(0, 1), a2 + hstepA, voffA);
;             PG8_WAIT_V(8); PG8_WAIT_L(0); PG8_BAR; PG8_MMA(0, 0, At, B0); PG8_MMA(0, 1, At, B1); PG8_BAR; PG8_SCHED;
;             PG8_LDA(At, 1, 1); PG8_STAGE(PG8_SB(1, 0), b3, voffB); PG8_STAGE(PG8_SB(1, 1), b3 + hstepB, voffB); PG8_STAGE(PG8_SA(1, 0), a3, voffA);
;             PG8_WAIT_V(8); PG8_WAIT_L(0); PG8_BAR; PG8_MMA(1, 0, At, B0); PG8_MMA(1, 1, At, B1); PG8_BAR; PG8_SCHED;
	s_add_i32 s33, 0, 0x18000
	s_add_i32 s57, 0, 0x1c000
	v_add_u32_e32 v162, s33, v149
	v_add_u32_e32 v175, s57, v149
	s_add_u32 s42, s42, 0x40000
	s_addc_u32 s43, s43, 0
	s_mov_b32 m0, s31
	v_lshl_add_u64 v[224:225], s[42:43], 0, v[134:135]
	global_load_lds_dwordx4 v[224:225], off
	v_lshl_add_u64 v[224:225], s[42:43], 0, v[130:131]
	s_mov_b32 m0, s35
	s_nop 0
	global_load_lds_dwordx4 v[224:225], off
	ds_read_b128 v[144:147], v162
	ds_read_b128 v[154:157], v162 offset:1024
	ds_read_b128 v[158:161], v162 offset:2048
	ds_read_b128 v[162:165], v162 offset:3072
	ds_read_b128 v[166:169], v175
	ds_read_b128 v[170:173], v175 offset:1024
	ds_read_b128 v[176:179], v175 offset:2048
	ds_read_b128 v[180:183], v175 offset:3072
	ds_read_b128 v[184:187], v153 offset:32768
	ds_read_b128 v[188:191], v153 offset:33792
	ds_read_b128 v[192:195], v153 offset:34816
	ds_read_b128 v[196:199], v153 offset:35840
	ds_read_b128 v[200:203], v153 offset:36864
	ds_read_b128 v[204:207], v153 offset:37888
	ds_read_b128 v[208:211], v153 offset:38912
	ds_read_b128 v[212:215], v153 offset:39936
	s_waitcnt vmcnt(16)
	s_waitcnt lgkmcnt(0)
	s_barrier
	s_setprio 1
	s_waitcnt lgkmcnt(0)
	v_mfma_f32_16x16x32_bf16 v[124:127], v[144:147], v[184:187], v[124:127]
	v_mfma_f32_16x16x32_bf16 v[120:123], v[158:161], v[184:187], v[120:123]
	v_mfma_f32_16x16x32_bf16 v[108:111], v[144:147], v[192:195], v[108:111]
	v_mfma_f32_16x16x32_bf16 v[104:107], v[158:161], v[192:195], v[104:107]
	v_mfma_f32_16x16x32_bf16 v[92:95], v[144:147], v[200:203], v[92:95]
	v_mfma_f32_16x16x32_bf16 v[88:91], v[158:161], v[200:203], v[88:91]
	v_mfma_f32_16x16x32_bf16 v[76:79], v[144:147], v[208:211], v[76:79]
	v_mfma_f32_16x16x32_bf16 v[72:75], v[158:161], v[208:211], v[72:75]
	v_mfma_f32_16x16x32_bf16 v[124:127], v[154:157], v[188:191], v[124:127]
	v_mfma_f32_16x16x32_bf16 v[120:123], v[162:165], v[188:191], v[120:123]
	v_mfma_f32_16x16x32_bf16 v[108:111], v[154:157], v[196:199], v[108:111]
	v_mfma_f32_16x16x32_bf16 v[104:107], v[162:165], v[196:199], v[104:107]
	v_mfma_f32_16x16x32_bf16 v[92:95], v[154:157], v[204:207], v[92:95]
	v_mfma_f32_16x16x32_bf16 v[88:91], v[162:165], v[204:207], v[88:91]
	v_mfma_f32_16x16x32_bf16 v[76:79], v[154:157], v[212:215], v[76:79]
	v_mfma_f32_16x16x32_bf16 v[72:75], v[162:165], v[212:215], v[72:75]
	s_setprio 0
	s_setprio 1
	v_mfma_f32_16x16x32_bf16 v[116:119], v[166:169], v[184:187], v[116:119]
	v_mfma_f32_16x16x32_bf16 v[112:115], v[176:179], v[184:187], v[112:115]
	v_mfma_f32_16x16x32_bf16 v[100:103], v[166:169], v[192:195], v[100:103]
	v_mfma_f32_16x16x32_bf16 v[96:99], v[176:179], v[192:195], v[96:99]
	v_mfma_f32_16x16x32_bf16 v[84:87], v[166:169], v[200:203], v[84:87]
	v_mfma_f32_16x16x32_bf16 v[80:83], v[176:179], v[200:203], v[80:83]
	v_mfma_f32_16x16x32_bf16 v[68:71], v[166:169], v[208:211], v[68:71]
	v_mfma_f32_16x16x32_bf16 v[64:67], v[176:179], v[208:211], v[64:67]
	v_mfma_f32_16x16x32_bf16 v[116:119], v[170:173], v[188:191], v[116:119]
	v_mfma_f32_16x16x32_bf16 v[112:115], v[180:183], v[188:191], v[112:115]
	v_mfma_f32_16x16x32_bf16 v[100:103], v[170:173], v[196:199], v[100:103]
	v_mfma_f32_16x16x32_bf16 v[96:99], v[180:183], v[196:199], v[96:99]
	v_mfma_f32_16x16x32_bf16 v[84:87], v[170:173], v[204:207], v[84:87]
	v_mfma_f32_16x16x32_bf16 v[80:83], v[180:183], v[204:207], v[80:83]
	v_mfma_f32_16x16x32_bf16 v[68:71], v[170:173], v[212:215], v[68:71]
	v_mfma_f32_16x16x32_bf16 v[64:67], v[180:183], v[212:215], v[64:67]
	s_setprio 0
	s_barrier
; #define PG8_STAGE(bufoff, gbase, voff) do { _Pragma("unroll") for (int _i = 0; _i < 2; ++_i) \
;         __builtin_amdgcn_global_load_lds((const unsigned*)((const char*)(gbase) + (voff)[_i]), (PG8_LAS unsigned*)(lds + (bufoff) + ldsw + _i * 8192), 16, 0, 0); } while (0)
; #define PG8_LDA(dst, b, h) do { _Pragma("unroll") for (int m = 0; m < 4; ++m) _Pragma("unroll") for (int k = 0; k < 2; ++k) dst[m][k] = *(const PG8_LAS bf16x8*)(lds + PG8_SA(b, h) + aoff + m * 2048 + k * 1024); } while (0)
; #define PG8_LDB(dst, b, h) do { _Pragma("unroll") for (int n = 0; n < 2; ++n) _Pragma("unroll") for (int k = 0; k < 2; ++k) dst[n][k] = *(const PG8_LAS bf16x8*)(lds + PG8_SB(b, h) + boff + n * 2048 + k * 1024); } while (0)
; #define PG8_MMA(ai, bj, At, Bt) do { __builtin_amdgcn_s_setprio(1); _Pragma("unroll") for (int m = 0; m < 4; ++m) _Pragma("unroll") for (int n = 0; n < 2; ++n) _Pragma("unroll") for (int k = 0; k < 2; ++k) \
;         acc[ai][bj][m][n] = __builtin_amdgcn_mfma_f32_16x16x32_bf16(Bt[n][k], At[m][k], acc[ai][bj][m][n], 0, 0, 0); __builtin_amdgcn_s_setprio(0); } while (0)
; #define PG8_WAIT_V(n) asm volatile("s_waitcnt vmcnt(" #n ")" ::: "memory")
; template <class Epi, class Sched, bool ALIGN_EPI = false, bool SP2 = false>
; __device__ __forceinline__ void gemm_phase(PG8_LAS unsigned char* lds, const Gemm g, const Sched& S, const Epi& E) {
;     ...
;             PG8_LDB(B0, 0, 0); PG8_LDB(B1, 0, 1); PG8_SCHED; PG8_LDA(At, 0, 0); PG8_STAGE(PG8_SA(1, 1), a1 + hstepA, voffA);
;             PG8_WAIT_V(8); PG8_WAIT_L(0); PG8_BAR; PG8_MMA(0, 0, At, B0); PG8_MMA(0, 1, At, B1); PG8_BAR; PG8_SCHED;
;             PG8_LDA(At, 0, 1); PG8_STAGE(PG8_SB(0, 0), b2, voffB); PG8_STAGE(PG8_SB(0, 1), b2 + hstepB, voffB); PG8_STAGE(PG8_SA(0, 0), a2, voffA);
;             PG8_WAIT_V(8); PG8_WAIT_L(0); PG8_BAR; PG8_MMA(1, 0, At, B0); PG8_MMA(1, 1, At, B1); PG8_BAR; PG8_SCHED;
;             PG8_LDB(B0, 1, 0); PG8_LDB(B1, 1, 1); PG8_SCHED; PG8_LDA(At, 1, 0); PG8_STAGE(PG8_SA(0, 1), a2 + hstepA, voffA);
;             PG8_WAIT_V(8); PG8_WAIT_L(0); PG8_BAR; PG8_MMA(0, 0, At, B0); PG8_MMA(0, 1, At, B1); PG8_BAR; PG8_SCHED;
;             PG8_LDA(At, 1, 1); PG8_STAGE(PG8_SB(1, 0), b3, voffB); PG8_STAGE(PG8_SB(1, 1), b3 + hstepB, voffB); PG8_STAGE(PG8_SA(1, 0), a3, voffA);
;             PG8_WAIT_V(8); PG8_WAIT_L(0); PG8_BAR; PG8_MMA(1, 0, At, B0); PG8_MMA(1, 1, At, B1); PG8_BAR; PG8_SCHED;
	s_add_i32 s33, s33, s22
	v_lshl_add_u64 v[216:217], v[216:217], 0, s[6:7]
	s_mov_b32 m0, s33
	s_nop 0
	global_load_lds_dwordx4 v[216:217], off
	s_add_i32 m0, s33, 0x2000
	s_add_u32 s40, s40, 0x40080
	v_lshl_add_u64 v[216:217], v[218:219], 0, s[6:7]
	s_addc_u32 s41, s41, 0
	s_add_i32 s33, s57, s22
	global_load_lds_dwordx4 v[216:217], off
	v_lshl_add_u64 v[216:217], s[40:41], 0, v[132:133]
	s_mov_b32 m0, s33
	s_nop 0
	global_load_lds_dwordx4 v[216:217], off
	v_lshl_add_u64 v[216:217], s[40:41], 0, v[128:129]
	s_add_i32 m0, s33, 0x2000
	s_nop 0
	global_load_lds_dwordx4 v[216:217], off
	v_lshl_add_u64 v[216:217], v[220:221], 0, s[6:7]
	s_mov_b32 m0, s44
	s_nop 0
	global_load_lds_dwordx4 v[216:217], off
	v_lshl_add_u64 v[216:217], v[222:223], 0, s[6:7]
	s_mov_b32 m0, s45
	s_nop 0
	global_load_lds_dwordx4 v[216:217], off
	ds_read_b128 v[184:187], v153 offset:49152
	ds_read_b128 v[188:191], v153 offset:50176
	ds_read_b128 v[192:195], v153 offset:51200
	ds_read_b128 v[196:199], v153 offset:52224
	ds_read_b128 v[200:203], v153 offset:53248
	ds_read_b128 v[204:207], v153 offset:54272
	ds_read_b128 v[208:211], v153 offset:55296
	ds_read_b128 v[212:215], v153 offset:56320
	s_waitcnt vmcnt(8)
	s_waitcnt lgkmcnt(0)
	s_barrier
	s_setprio 1
	s_waitcnt lgkmcnt(0)
	v_mfma_f32_16x16x32_bf16 v[60:63], v[144:147], v[184:187], v[60:63]
	v_mfma_f32_16x16x32_bf16 v[56:59], v[158:161], v[184:187], v[56:59]
	v_mfma_f32_16x16x32_bf16 v[44:47], v[144:147], v[192:195], v[44:47]
	v_mfma_f32_16x16x32_bf16 v[40:43], v[158:161], v[192:195], v[40:43]
	v_mfma_f32_16x16x32_bf16 v[28:31], v[144:147], v[200:203], v[28:31]
	v_mfma_f32_16x16x32_bf16 v[24:27], v[158:161], v[200:203], v[24:27]
	v_mfma_f32_16x16x32_bf16 v[12:15], v[144:147], v[208:211], v[12:15]
	v_mfma_f32_16x16x32_bf16 v[8:11], v[158:161], v[208:211], v[8:11]
	v_mfma_f32_16x16x32_bf16 v[60:63], v[154:157], v[188:191], v[60:63]
	v_mfma_f32_16x16x32_bf16 v[56:59], v[162:165], v[188:191], v[56:59]
	v_mfma_f32_16x16x32_bf16 v[44:47], v[154:157], v[196:199], v[44:47]
	v_mfma_f32_16x16x32_bf16 v[40:43], v[162:165], v[196:199], v[40:43]
	v_mfma_f32_16x16x32_bf16 v[28:31], v[154:157], v[204:207], v[28:31]
	v_mfma_f32_16x16x32_bf16 v[24:27], v[162:165], v[204:207], v[24:27]
	v_mfma_f32_16x16x32_bf16 v[12:15], v[154:157], v[212:215], v[12:15]
	v_mfma_f32_16x16x32_bf16 v[8:11], v[162:165], v[212:215], v[8:11]
	s_setprio 0
	s_setprio 1
	v_mfma_f32_16x16x32_bf16 v[52:55], v[166:169], v[184:187], v[52:55]
	v_mfma_f32_16x16x32_bf16 v[48:51], v[176:179], v[184:187], v[48:51]
	v_mfma_f32_16x16x32_bf16 v[36:39], v[166:169], v[192:195], v[36:39]
	v_mfma_f32_16x16x32_bf16 v[32:35], v[176:179], v[192:195], v[32:35]
	v_mfma_f32_16x16x32_bf16 v[20:23], v[166:169], v[200:203], v[20:23]
	v_mfma_f32_16x16x32_bf16 v[16:19], v[176:179], v[200:203], v[16:19]
	v_mfma_f32_16x16x32_bf16 v[4:7], v[166:169], v[208:211], v[4:7]
	v_mfma_f32_16x16x32_bf16 v[0:3], v[176:179], v[208:211], v[0:3]
	v_mfma_f32_16x16x32_bf16 v[52:55], v[170:173], v[188:191], v[52:55]
	v_mfma_f32_16x16x32_bf16 v[48:51], v[180:183], v[188:191], v[48:51]
	v_mfma_f32_16x16x32_bf16 v[36:39], v[170:173], v[196:199], v[36:39]
	v_mfma_f32_16x16x32_bf16 v[32:35], v[180:183], v[196:199], v[32:35]
	v_mfma_f32_16x16x32_bf16 v[20:23], v[170:173], v[204:207], v[20:23]
	v_mfma_f32_16x16x32_bf16 v[16:19], v[180:183], v[204:207], v[16:19]
	v_mfma_f32_16x16x32_bf16 v[4:7], v[170:173], v[212:215], v[4:7]
	v_mfma_f32_16x16x32_bf16 v[0:3], v[180:183], v[212:215], v[0:3]
	s_setprio 0
	s_barrier
	s_add_i32 s56, s56, 2
	s_add_u32 s38, s38, 0x100
	s_addc_u32 s39, s39, 0
	s_add_u32 s54, s54, 0x100
	s_addc_u32 s55, s55, 0
	s_cmp_gt_u32 s56, 13
	s_branch .LBB0_605

; #define PG8_STAGE(bufoff, gbase, voff) do { _Pragma("unroll") for (int _i = 0; _i < 2; ++_i) \
;         __builtin_amdgcn_global_load_lds((const unsigned*)((const char*)(gbase) + (voff)[_i]), (PG8_LAS unsigned*)(lds + (bufoff) + ldsw + _i * 8192), 16, 0, 0); } while (0)
; #define PG8_LDA(dst, b, h) do { _Pragma("unroll") for (int m = 0; m < 4; ++m) _Pragma("unroll") for (int k = 0; k < 2; ++k) dst[m][k] = *(const PG8_LAS bf16x8*)(lds + PG8_SA(b, h) + aoff + m * 2048 + k * 1024); } while (0)
; #define PG8_LDB(dst, b, h) do { _Pragma("unroll") for (int n = 0; n < 2; ++n) _Pragma("unroll") for (int k = 0; k < 2; ++k) dst[n][k] = *(const PG8_LAS bf16x8*)(lds + PG8_SB(b, h) + boff + n * 2048 + k * 1024); } while (0)
; #define PG8_MMA(ai, bj, At, Bt) do { __builtin_amdgcn_s_setprio(1); _Pragma("unroll") for (int m = 0; m < 4; ++m) _Pragma("unroll") for (int n = 0; n < 2; ++n) _Pragma("unroll") for (int k = 0; k < 2; ++k) \
;         acc[ai][bj][m][n] = __builtin_amdgcn_mfma_f32_16x16x32_bf16(Bt[n][k], At[m][k], acc[ai][bj][m][n], 0, 0, 0); __builtin_amdgcn_s_setprio(0); } while (0)
; #define PG8_WAIT_V(n) asm volatile("s_waitcnt vmcnt(" #n ")" ::: "memory")
; template <class Epi, class Sched, bool ALIGN_EPI = false, bool SP2 = false>
; __device__ __forceinline__ void gemm_phase(PG8_LAS unsigned char* lds, const Gemm g, const Sched& S, const Epi& E) {
;     ...
;             PG8_LDB(B0, 0, 0); PG8_LDB(B1, 0, 1); PG8_SCHED; PG8_LDA(At, 0, 0); PG8_STAGE(PG8_SA(1, 1), a1 + hstepA, voffA);
;             PG8_WAIT_V(8); PG8_WAIT_L(0); PG8_BAR; PG8_MMA(0, 0, At, B0); PG8_MMA(0, 1, At, B1); PG8_BAR; PG8_SCHED;
;             PG8_LDA(At, 0, 1); PG8_STAGE(PG8_SB(0, 0), b2, voffB); PG8_STAGE(PG8_SB(0, 1), b2 + hstepB, voffB); PG8_STAGE(PG8_SA(0, 0), a2, voffA);
;             PG8_WAIT_V(8); PG8_WAIT_L(0); PG8_BAR; PG8_MMA(1, 0, At, B0); PG8_MMA(1, 1, At, B1); PG8_BAR; PG8_SCHED;
;             PG8_LDB(B0, 1, 0); PG8_LDB(B1, 1, 1); PG8_SCHED; PG8_LDA(At, 1, 0); PG8_STAGE(PG8_SA(0, 1), a2 + hstepA, voffA);
;             PG8_WAIT_V(8); PG8_WAIT_L(0); PG8_BAR; PG8_MMA(0, 0, At, B0); PG8_MMA(0, 1, At, B1); PG8_BAR; PG8_SCHED;
;             PG8_LDA(At, 1, 1); PG8_STAGE(PG8_SB(1, 0), b3, voffB); PG8_STAGE(PG8_SB(1, 1), b3 + hstepB, voffB); PG8_STAGE(PG8_SA(1, 0), a3, voffA);
;             PG8_WAIT_V(8); PG8_WAIT_L(0); PG8_BAR; PG8_MMA(1, 0, At, B0); PG8_MMA(1, 1, At, B1); PG8_BAR; PG8_SCHED;
.LBB0_685:
	s_add_u32 s38, s36, 0x100
	s_addc_u32 s39, s37, 0
	s_cmp_eq_u32 s62, 40
	s_cselect_b32 s43, s5, s39
	s_cselect_b32 s42, s4, s38
	s_cselect_b32 s41, s25, s61
	s_cselect_b32 s40, s24, s60
	v_lshl_add_u64 v[164:165], s[36:37], 0, v[152:153]
	s_add_i32 m0, s28, 0xc000
	s_nop 0
	global_load_lds_dwordx4 v[164:165], off
	v_lshl_add_u64 v[164:165], s[36:37], 0, v[154:155]
	s_add_i32 m0, s28, 0xe000
	s_nop 0
	global_load_lds_dwordx4 v[164:165], off
	ds_read_b128 v[128:131], v169
	ds_read_b128 v[132:135], v169 offset:1024
	ds_read_b128 v[136:139], v169 offset:2048
	ds_read_b128 v[140:143], v169 offset:3072
	ds_read_b128 v[160:163], v170
	ds_read_b128 v[176:179], v170 offset:1024
	ds_read_b128 v[180:183], v170 offset:2048
	ds_read_b128 v[184:187], v170 offset:3072
	ds_read_b128 v[188:191], v171
	ds_read_b128 v[192:195], v171 offset:1024
	ds_read_b128 v[196:199], v171 offset:2048
	ds_read_b128 v[200:203], v171 offset:3072
	ds_read_b128 v[204:207], v171 offset:4096
	ds_read_b128 v[208:211], v171 offset:5120
	ds_read_b128 v[212:215], v171 offset:6144
	ds_read_b128 v[216:219], v171 offset:7168
	s_waitcnt vmcnt(8)
	s_waitcnt lgkmcnt(0)
	s_barrier
	s_setprio 1
	s_waitcnt lgkmcnt(0)
	v_mfma_f32_16x16x32_bf16 v[124:127], v[128:131], v[188:191], v[124:127]
	v_mfma_f32_16x16x32_bf16 v[120:123], v[136:139], v[188:191], v[120:123]
	v_mfma_f32_16x16x32_bf16 v[116:119], v[128:131], v[196:199], v[116:119]
	v_mfma_f32_16x16x32_bf16 v[112:115], v[136:139], v[196:199], v[112:115]
	v_mfma_f32_16x16x32_bf16 v[108:111], v[128:131], v[204:207], v[108:111]
	v_mfma_f32_16x16x32_bf16 v[104:107], v[136:139], v[204:207], v[104:107]
	v_mfma_f32_16x16x32_bf16 v[100:103], v[128:131], v[212:215], v[100:103]
	v_mfma_f32_16x16x32_bf16 v[96:99], v[136:139], v[212:215], v[96:99]
	v_mfma_f32_16x16x32_bf16 v[124:127], v[132:135], v[192:195], v[124:127]
	v_mfma_f32_16x16x32_bf16 v[120:123], v[140:143], v[192:195], v[120:123]
	v_mfma_f32_16x16x32_bf16 v[116:119], v[132:135], v[200:203], v[116:119]
	v_mfma_f32_16x16x32_bf16 v[112:115], v[140:143], v[200:203], v[112:115]
	v_mfma_f32_16x16x32_bf16 v[108:111], v[132:135], v[208:211], v[108:111]
	v_mfma_f32_16x16x32_bf16 v[104:107], v[140:143], v[208:211], v[104:107]
	v_mfma_f32_16x16x32_bf16 v[100:103], v[132:135], v[216:219], v[100:103]
	v_mfma_f32_16x16x32_bf16 v[96:99], v[140:143], v[216:219], v[96:99]
	s_setprio 0
	s_setprio 1
	v_mfma_f32_16x16x32_bf16 v[68:71], v[160:163], v[188:191], v[68:71]
	v_mfma_f32_16x16x32_bf16 v[64:67], v[180:183], v[188:191], v[64:67]
	v_mfma_f32_16x16x32_bf16 v[52:55], v[160:163], v[196:199], v[52:55]
	v_mfma_f32_16x16x32_bf16 v[48:51], v[180:183], v[196:199], v[48:51]
	v_mfma_f32_16x16x32_bf16 v[44:47], v[160:163], v[204:207], v[44:47]
	v_mfma_f32_16x16x32_bf16 v[40:43], v[180:183], v[204:207], v[40:43]
	v_mfma_f32_16x16x32_bf16 v[36:39], v[160:163], v[212:215], v[36:39]
	v_mfma_f32_16x16x32_bf16 v[32:35], v[180:183], v[212:215], v[32:35]
	v_mfma_f32_16x16x32_bf16 v[68:71], v[176:179], v[192:195], v[68:71]
	v_mfma_f32_16x16x32_bf16 v[64:67], v[184:187], v[192:195], v[64:67]
	v_mfma_f32_16x16x32_bf16 v[52:55], v[176:179], v[200:203], v[52:55]
	v_mfma_f32_16x16x32_bf16 v[48:51], v[184:187], v[200:203], v[48:51]
	v_mfma_f32_16x16x32_bf16 v[44:47], v[176:179], v[208:211], v[44:47]
	v_mfma_f32_16x16x32_bf16 v[40:43], v[184:187], v[208:211], v[40:43]
	v_mfma_f32_16x16x32_bf16 v[36:39], v[176:179], v[216:219], v[36:39]
	v_mfma_f32_16x16x32_bf16 v[32:35], v[184:187], v[216:219], v[32:35]
	s_setprio 0
	s_barrier
	s_add_i32 s33, s50, s23
	v_lshl_add_u64 v[164:165], s[40:41], 0, v[146:147]
	s_mov_b32 m0, s33
	s_nop 0
	global_load_lds_dwordx4 v[164:165], off
	s_add_i32 m0, s33, 0x2000
	s_add_u32 s36, s40, 0xb0000
	v_lshl_add_u64 v[172:173], s[40:41], 0, v[150:151]
	s_addc_u32 s37, s41, 0
	s_add_i32 s33, s51, s23
	global_load_lds_dwordx4 v[172:173], off
	v_lshl_add_u64 v[220:221], s[36:37], 0, v[146:147]
	s_mov_b32 m0, s33
	v_lshl_add_u64 v[222:223], s[42:43], 0, v[148:149]
	global_load_lds_dwordx4 v[220:221], off
	v_lshl_add_u64 v[220:221], s[36:37], 0, v[150:151]
	s_add_i32 m0, s33, 0x2000
	s_nop 0
	global_load_lds_dwordx4 v[220:221], off
	v_lshl_add_u64 v[220:221], s[42:43], 0, v[144:145]
	s_mov_b32 m0, s28
	s_nop 0
	global_load_lds_dwordx4 v[220:221], off
	s_mov_b32 m0, s29
	s_nop 0
	global_load_lds_dwordx4 v[222:223], off
	ds_read_b128 v[188:191], v171 offset:16384
	ds_read_b128 v[192:195], v171 offset:17408
	ds_read_b128 v[196:199], v171 offset:18432
	ds_read_b128 v[200:203], v171 offset:19456
	ds_read_b128 v[204:207], v171 offset:20480
	ds_read_b128 v[208:211], v171 offset:21504
	ds_read_b128 v[212:215], v171 offset:22528
	ds_read_b128 v[216:219], v171 offset:23552
	s_waitcnt vmcnt(8)
	s_waitcnt lgkmcnt(0)
	s_barrier
; #define PG8_STAGE(bufoff, gbase, voff) do { _Pragma("unroll") for (int _i = 0; _i < 2; ++_i) \
;         __builtin_amdgcn_global_load_lds((const unsigned*)((const char*)(gbase) + (voff)[_i]), (PG8_LAS unsigned*)(lds + (bufoff) + ldsw + _i * 8192), 16, 0, 0); } while (0)
; #define PG8_LDA(dst, b, h) do { _Pragma("unroll") for (int m = 0; m < 4; ++m) _Pragma("unroll") for (int k = 0; k < 2; ++k) dst[m][k] = *(const PG8_LAS bf16x8*)(lds + PG8_SA(b, h) + aoff + m * 2048 + k * 1024); } while (0)
; #define PG8_LDB(dst, b, h) do { _Pragma("unroll") for (int n = 0; n < 2; ++n) _Pragma("unroll") for (int k = 0; k < 2; ++k) dst[n][k] = *(const PG8_LAS bf16x8*)(lds + PG8_SB(b, h) + boff + n * 2048 + k * 1024); } while (0)
; #define PG8_MMA(ai, bj, At, Bt) do { __builtin_amdgcn_s_setprio(1); _Pragma("unroll") for (int m = 0; m < 4; ++m) _Pragma("unroll") for (int n = 0; n < 2; ++n) _Pragma("unroll") for (int k = 0; k < 2; ++k) \
;         acc[ai][bj][m][n] = __builtin_amdgcn_mfma_f32_16x16x32_bf16(Bt[n][k], At[m][k], acc[ai][bj][m][n], 0, 0, 0); __builtin_amdgcn_s_setprio(0); } while (0)
; #define PG8_WAIT_V(n) asm volatile("s_waitcnt vmcnt(" #n ")" ::: "memory")
; #define PG8_WAIT_L(n) asm volatile("s_waitcnt lgkmcnt(" #n ")" ::: "memory")
; #define PG8_BAR __builtin_amdgcn_s_barrier()
; #define PG8_SCHED __builtin_amdgcn_sched_barrier(0)
; template <class Epi, class Sched, bool ALIGN_EPI = false, bool SP2 = false>
; __device__ __forceinline__ void gemm_phase(PG8_LAS unsigned char* lds, const Gemm g, const Sched& S, const Epi& E) {
;     ...
;             PG8_WAIT_V(8); PG8_WAIT_L(0); PG8_BAR; PG8_MMA(1, 0, At, B0); PG8_MMA(1, 1, At, B1); PG8_BAR; PG8_SCHED;
;             PG8_LDB(B0, 1, 0); PG8_LDB(B1, 1, 1); PG8_SCHED; PG8_LDA(At, 1, 0); PG8_STAGE(PG8_SA(0, 1), a2 + hstepA, voffA);
;             PG8_WAIT_V(8); PG8_WAIT_L(0); PG8_BAR; PG8_MMA(0, 0, At, B0); PG8_MMA(0, 1, At, B1); PG8_BAR; PG8_SCHED;
	s_setprio 1
	s_waitcnt lgkmcnt(0)
	v_mfma_f32_16x16x32_bf16 v[92:95], v[128:131], v[188:191], v[92:95]
	v_mfma_f32_16x16x32_bf16 v[88:91], v[136:139], v[188:191], v[88:91]
	v_mfma_f32_16x16x32_bf16 v[84:87], v[128:131], v[196:199], v[84:87]
	v_mfma_f32_16x16x32_bf16 v[80:83], v[136:139], v[196:199], v[80:83]
	v_mfma_f32_16x16x32_bf16 v[76:79], v[128:131], v[204:207], v[76:79]
	v_mfma_f32_16x16x32_bf16 v[72:75], v[136:139], v[204:207], v[72:75]
	v_mfma_f32_16x16x32_bf16 v[60:63], v[128:131], v[212:215], v[60:63]
	v_mfma_f32_16x16x32_bf16 v[56:59], v[136:139], v[212:215], v[56:59]
	v_mfma_f32_16x16x32_bf16 v[92:95], v[132:135], v[192:195], v[92:95]
	v_mfma_f32_16x16x32_bf16 v[88:91], v[140:143], v[192:195], v[88:91]
	v_mfma_f32_16x16x32_bf16 v[84:87], v[132:135], v[200:203], v[84:87]
	v_mfma_f32_16x16x32_bf16 v[80:83], v[140:143], v[200:203], v[80:83]
	v_mfma_f32_16x16x32_bf16 v[76:79], v[132:135], v[208:211], v[76:79]
	v_mfma_f32_16x16x32_bf16 v[72:75], v[140:143], v[208:211], v[72:75]
	v_mfma_f32_16x16x32_bf16 v[60:63], v[132:135], v[216:219], v[60:63]
	v_mfma_f32_16x16x32_bf16 v[56:59], v[140:143], v[216:219], v[56:59]
	s_setprio 0
	s_setprio 1
	v_mfma_f32_16x16x32_bf16 v[28:31], v[160:163], v[188:191], v[28:31]
	v_mfma_f32_16x16x32_bf16 v[24:27], v[180:183], v[188:191], v[24:27]
	v_mfma_f32_16x16x32_bf16 v[20:23], v[160:163], v[196:199], v[20:23]
	v_mfma_f32_16x16x32_bf16 v[16:19], v[180:183], v[196:199], v[16:19]
	v_mfma_f32_16x16x32_bf16 v[12:15], v[160:163], v[204:207], v[12:15]
	v_mfma_f32_16x16x32_bf16 v[8:11], v[180:183], v[204:207], v[8:11]
	v_mfma_f32_16x16x32_bf16 v[4:7], v[160:163], v[212:215], v[4:7]
	v_mfma_f32_16x16x32_bf16 v[0:3], v[180:183], v[212:215], v[0:3]
	v_mfma_f32_16x16x32_bf16 v[28:31], v[176:179], v[192:195], v[28:31]
	v_mfma_f32_16x16x32_bf16 v[24:27], v[184:187], v[192:195], v[24:27]
	v_mfma_f32_16x16x32_bf16 v[20:23], v[176:179], v[200:203], v[20:23]
	v_mfma_f32_16x16x32_bf16 v[16:19], v[184:187], v[200:203], v[16:19]
	v_mfma_f32_16x16x32_bf16 v[12:15], v[176:179], v[208:211], v[12:15]
	v_mfma_f32_16x16x32_bf16 v[8:11], v[184:187], v[208:211], v[8:11]
	v_mfma_f32_16x16x32_bf16 v[4:7], v[176:179], v[216:219], v[4:7]
	v_mfma_f32_16x16x32_bf16 v[0:3], v[184:187], v[216:219], v[0:3]
	s_setprio 0
	s_barrier
	s_add_i32 s33, 0, 0x18000
	s_add_i32 s63, 0, 0x1c000
	v_add_u32_e32 v140, s33, v167
	v_add_u32_e32 v175, s63, v167
	s_add_u32 s36, s42, 0xb0000
	s_addc_u32 s37, s43, 0
	s_mov_b32 m0, s30
	v_lshl_add_u64 v[224:225], s[36:37], 0, v[144:145]
	global_load_lds_dwordx4 v[224:225], off
	v_lshl_add_u64 v[224:225], s[36:37], 0, v[148:149]
	s_mov_b32 m0, s31
	s_nop 0
	global_load_lds_dwordx4 v[224:225], off
	ds_read_b128 v[128:131], v140
	ds_read_b128 v[132:135], v140 offset:1024
	ds_read_b128 v[136:139], v140 offset:2048
	ds_read_b128 v[140:143], v140 offset:3072
	ds_read_b128 v[160:163], v175
	ds_read_b128 v[176:179], v175 offset:1024
	ds_read_b128 v[180:183], v175 offset:2048
	ds_read_b128 v[184:187], v175 offset:3072
	ds_read_b128 v[188:191], v171 offset:32768
	ds_read_b128 v[192:195], v171 offset:33792
	ds_read_b128 v[196:199], v171 offset:34816
	ds_read_b128 v[200:203], v171 offset:35840
	ds_read_b128 v[204:207], v171 offset:36864
	ds_read_b128 v[208:211], v171 offset:37888
	ds_read_b128 v[212:215], v171 offset:38912
	ds_read_b128 v[216:219], v171 offset:39936
	s_waitcnt vmcnt(8)
	s_waitcnt lgkmcnt(0)
	s_barrier
	s_setprio 1
	s_waitcnt lgkmcnt(0)
	v_mfma_f32_16x16x32_bf16 v[124:127], v[128:131], v[188:191], v[124:127]
	v_mfma_f32_16x16x32_bf16 v[120:123], v[136:139], v[188:191], v[120:123]
	v_mfma_f32_16x16x32_bf16 v[116:119], v[128:131], v[196:199], v[116:119]
	v_mfma_f32_16x16x32_bf16 v[112:115], v[136:139], v[196:199], v[112:115]
	v_mfma_f32_16x16x32_bf16 v[108:111], v[128:131], v[204:207], v[108:111]
	v_mfma_f32_16x16x32_bf16 v[104:107], v[136:139], v[204:207], v[104:107]
	v_mfma_f32_16x16x32_bf16 v[100:103], v[128:131], v[212:215], v[100:103]
	v_mfma_f32_16x16x32_bf16 v[96:99], v[136:139], v[212:215], v[96:99]
	v_mfma_f32_16x16x32_bf16 v[124:127], v[132:135], v[192:195], v[124:127]
	v_mfma_f32_16x16x32_bf16 v[120:123], v[140:143], v[192:195], v[120:123]
	v_mfma_f32_16x16x32_bf16 v[116:119], v[132:135], v[200:203], v[116:119]
	v_mfma_f32_16x16x32_bf16 v[112:115], v[140:143], v[200:203], v[112:115]
	v_mfma_f32_16x16x32_bf16 v[108:111], v[132:135], v[208:211], v[108:111]
	v_mfma_f32_16x16x32_bf16 v[104:107], v[140:143], v[208:211], v[104:107]
	v_mfma_f32_16x16x32_bf16 v[100:103], v[132:135], v[216:219], v[100:103]
	v_mfma_f32_16x16x32_bf16 v[96:99], v[140:143], v[216:219], v[96:99]
	s_setprio 0
	s_setprio 1
	v_mfma_f32_16x16x32_bf16 v[68:71], v[160:163], v[188:191], v[68:71]
	v_mfma_f32_16x16x32_bf16 v[64:67], v[180:183], v[188:191], v[64:67]
	v_mfma_f32_16x16x32_bf16 v[52:55], v[160:163], v[196:199], v[52:55]
	v_mfma_f32_16x16x32_bf16 v[48:51], v[180:183], v[196:199], v[48:51]
	v_mfma_f32_16x16x32_bf16 v[44:47], v[160:163], v[204:207], v[44:47]
	v_mfma_f32_16x16x32_bf16 v[40:43], v[180:183], v[204:207], v[40:43]
	v_mfma_f32_16x16x32_bf16 v[36:39], v[160:163], v[212:215], v[36:39]
	v_mfma_f32_16x16x32_bf16 v[32:35], v[180:183], v[212:215], v[32:35]
	v_mfma_f32_16x16x32_bf16 v[68:71], v[176:179], v[192:195], v[68:71]
	v_mfma_f32_16x16x32_bf16 v[64:67], v[184:187], v[192:195], v[64:67]
	v_mfma_f32_16x16x32_bf16 v[52:55], v[176:179], v[200:203], v[52:55]
	v_mfma_f32_16x16x32_bf16 v[48:51], v[184:187], v[200:203], v[48:51]
	v_mfma_f32_16x16x32_bf16 v[44:47], v[176:179], v[208:211], v[44:47]
	v_mfma_f32_16x16x32_bf16 v[40:43], v[184:187], v[208:211], v[40:43]
	v_mfma_f32_16x16x32_bf16 v[36:39], v[176:179], v[216:219], v[36:39]
	v_mfma_f32_16x16x32_bf16 v[32:35], v[184:187], v[216:219], v[32:35]
	s_setprio 0
	s_barrier
; #define PG8_STAGE(bufoff, gbase, voff) do { _Pragma("unroll") for (int _i = 0; _i < 2; ++_i) \
;         __builtin_amdgcn_global_load_lds((const unsigned*)((const char*)(gbase) + (voff)[_i]), (PG8_LAS unsigned*)(lds + (bufoff) + ldsw + _i * 8192), 16, 0, 0); } while (0)
; #define PG8_LDA(dst, b, h) do { _Pragma("unroll") for (int m = 0; m < 4; ++m) _Pragma("unroll") for (int k = 0; k < 2; ++k) dst[m][k] = *(const PG8_LAS bf16x8*)(lds + PG8_SA(b, h) + aoff + m * 2048 + k * 1024); } while (0)
; #define PG8_MMA(ai, bj, At, Bt) do { __builtin_amdgcn_s_setprio(1); _Pragma("unroll") for (int m = 0; m < 4; ++m) _Pragma("unroll") for (int n = 0; n < 2; ++n) _Pragma("unroll") for (int k = 0; k < 2; ++k) \
;         acc[ai][bj][m][n] = __builtin_amdgcn_mfma_f32_16x16x32_bf16(Bt[n][k], At[m][k], acc[ai][bj][m][n], 0, 0, 0); __builtin_amdgcn_s_setprio(0); } while (0)
; #define PG8_WAIT_V(n) asm volatile("s_waitcnt vmcnt(" #n ")" ::: "memory")
; #define PG8_WAIT_L(n) asm volatile("s_waitcnt lgkmcnt(" #n ")" ::: "memory")
; #define PG8_BAR __builtin_amdgcn_s_barrier()
; #define PG8_SCHED __builtin_amdgcn_sched_barrier(0)
; template <class Epi, class Sched, bool ALIGN_EPI = false, bool SP2 = false>
; __device__ __forceinline__ void gemm_phase(PG8_LAS unsigned char* lds, const Gemm g, const Sched& S, const Epi& E) {
;     ...
;         for (int t = 0; t < nt; t += 2) {
;             const bool last = (t == nt - 2);
;             const char* a1 = cA + (size_t)(t + 1) * kstep;
;             const char* a2 = last ? nA : cA + (size_t)(t + 2) * kstep; const char* b2 = last ? nB : cB + (size_t)(t + 2) * kstep;
;     ...
;             PG8_LDA(At, 1, 1); PG8_STAGE(PG8_SB(1, 0), b3, voffB); PG8_STAGE(PG8_SB(1, 1), b3 + hstepB, voffB); PG8_STAGE(PG8_SA(1, 0), a3, voffA);
;             PG8_WAIT_V(8); PG8_WAIT_L(0); PG8_BAR; PG8_MMA(1, 0, At, B0); PG8_MMA(1, 1, At, B1); PG8_BAR; PG8_SCHED;
	s_add_i32 s33, s33, s23
	v_lshl_add_u64 v[164:165], v[164:165], 0, s[6:7]
	s_mov_b32 m0, s33
	s_nop 0
	global_load_lds_dwordx4 v[164:165], off
	s_add_i32 m0, s33, 0x2000
	s_add_u32 s36, s40, 0xb0080
	v_lshl_add_u64 v[164:165], v[172:173], 0, s[6:7]
	s_addc_u32 s37, s41, 0
	s_add_i32 s33, s63, s23
	global_load_lds_dwordx4 v[164:165], off
	v_lshl_add_u64 v[164:165], s[36:37], 0, v[146:147]
	s_mov_b32 m0, s33
	s_nop 0
	global_load_lds_dwordx4 v[164:165], off
	v_lshl_add_u64 v[164:165], s[36:37], 0, v[150:151]
	s_add_i32 m0, s33, 0x2000
	s_nop 0
	global_load_lds_dwordx4 v[164:165], off
	v_lshl_add_u64 v[164:165], v[220:221], 0, s[6:7]
	s_mov_b32 m0, s46
	s_nop 0
	global_load_lds_dwordx4 v[164:165], off
	v_lshl_add_u64 v[164:165], v[222:223], 0, s[6:7]
	s_mov_b32 m0, s47
	s_nop 0
	global_load_lds_dwordx4 v[164:165], off
	ds_read_b128 v[188:191], v171 offset:49152
	ds_read_b128 v[192:195], v171 offset:50176
	ds_read_b128 v[196:199], v171 offset:51200
	ds_read_b128 v[200:203], v171 offset:52224
	ds_read_b128 v[204:207], v171 offset:53248
	ds_read_b128 v[208:211], v171 offset:54272
	ds_read_b128 v[212:215], v171 offset:55296
	ds_read_b128 v[216:219], v171 offset:56320
	s_waitcnt vmcnt(8)
	s_waitcnt lgkmcnt(0)
	s_barrier
	s_setprio 1
	s_waitcnt lgkmcnt(0)
	v_mfma_f32_16x16x32_bf16 v[92:95], v[128:131], v[188:191], v[92:95]
	v_mfma_f32_16x16x32_bf16 v[88:91], v[136:139], v[188:191], v[88:91]
	v_mfma_f32_16x16x32_bf16 v[84:87], v[128:131], v[196:199], v[84:87]
	v_mfma_f32_16x16x32_bf16 v[80:83], v[136:139], v[196:199], v[80:83]
	v_mfma_f32_16x16x32_bf16 v[76:79], v[128:131], v[204:207], v[76:79]
	v_mfma_f32_16x16x32_bf16 v[72:75], v[136:139], v[204:207], v[72:75]
	v_mfma_f32_16x16x32_bf16 v[60:63], v[128:131], v[212:215], v[60:63]
	v_mfma_f32_16x16x32_bf16 v[56:59], v[136:139], v[212:215], v[56:59]
	v_mfma_f32_16x16x32_bf16 v[92:95], v[132:135], v[192:195], v[92:95]
	v_mfma_f32_16x16x32_bf16 v[88:91], v[140:143], v[192:195], v[88:91]
	v_mfma_f32_16x16x32_bf16 v[84:87], v[132:135], v[200:203], v[84:87]
	v_mfma_f32_16x16x32_bf16 v[80:83], v[140:143], v[200:203], v[80:83]
	v_mfma_f32_16x16x32_bf16 v[76:79], v[132:135], v[208:211], v[76:79]
	v_mfma_f32_16x16x32_bf16 v[72:75], v[140:143], v[208:211], v[72:75]
	v_mfma_f32_16x16x32_bf16 v[60:63], v[132:135], v[216:219], v[60:63]
	v_mfma_f32_16x16x32_bf16 v[56:59], v[140:143], v[216:219], v[56:59]
	s_setprio 0
	s_setprio 1
	v_mfma_f32_16x16x32_bf16 v[28:31], v[160:163], v[188:191], v[28:31]
	v_mfma_f32_16x16x32_bf16 v[24:27], v[180:183], v[188:191], v[24:27]
	v_mfma_f32_16x16x32_bf16 v[20:23], v[160:163], v[196:199], v[20:23]
	v_mfma_f32_16x16x32_bf16 v[16:19], v[180:183], v[196:199], v[16:19]
	v_mfma_f32_16x16x32_bf16 v[12:15], v[160:163], v[204:207], v[12:15]
	v_mfma_f32_16x16x32_bf16 v[8:11], v[180:183], v[204:207], v[8:11]
	v_mfma_f32_16x16x32_bf16 v[4:7], v[160:163], v[212:215], v[4:7]
	v_mfma_f32_16x16x32_bf16 v[0:3], v[180:183], v[212:215], v[0:3]
	v_mfma_f32_16x16x32_bf16 v[28:31], v[176:179], v[192:195], v[28:31]
	v_mfma_f32_16x16x32_bf16 v[24:27], v[184:187], v[192:195], v[24:27]
	v_mfma_f32_16x16x32_bf16 v[20:23], v[176:179], v[200:203], v[20:23]
	v_mfma_f32_16x16x32_bf16 v[16:19], v[184:187], v[200:203], v[16:19]
	v_mfma_f32_16x16x32_bf16 v[12:15], v[176:179], v[208:211], v[12:15]
	v_mfma_f32_16x16x32_bf16 v[8:11], v[184:187], v[208:211], v[8:11]
	v_mfma_f32_16x16x32_bf16 v[4:7], v[176:179], v[216:219], v[4:7]
	v_mfma_f32_16x16x32_bf16 v[0:3], v[184:187], v[216:219], v[0:3]
	s_setprio 0
	s_barrier
	s_add_i32 s62, s62, 2
	s_add_u32 s60, s60, 0x100
	s_addc_u32 s61, s61, 0
	s_cmp_gt_u32 s62, 41
	s_mov_b64 s[36:37], s[38:39]
	s_cbranch_scc0 .LBB0_685
	s_and_b64 vcc, exec, s[8:9]
	s_cbranch_vccz .LBB0_688
	s_barrier
